# GEMM main loops (in-proj, late in-proj/up-proj, out-proj): per-phase s_setprio 1/0 flips removed (64 instructions); nothing else changed
# speedup vs baseline: 1.0043x; 1.0043x over previous
; #define PG8_STAGE(bufoff, gbase, voff) do { _Pragma("unroll") for (int _i = 0; _i < 2; ++_i) \
;         __builtin_amdgcn_global_load_lds((const unsigned*)((const char*)(gbase) + (voff)[_i]), (LAS unsigned*)(lds + (bufoff) + ldsw + _i * 8192), 16, 0, 0); } while (0)
; #define PG8_LDA(dst, b, h) do { _Pragma("unroll") for (int m = 0; m < 4; ++m) _Pragma("unroll") for (int k = 0; k < 2; ++k) dst[m][k] = *(const LAS bf16x8*)(lds + PG8_SA(b, h) + aoff + m * 2048 + k * 1024); } while (0)
; #define PG8_LDB(dst, b, h) do { _Pragma("unroll") for (int n = 0; n < 2; ++n) _Pragma("unroll") for (int k = 0; k < 2; ++k) dst[n][k] = *(const LAS bf16x8*)(lds + PG8_SB(b, h) + boff + n * 2048 + k * 1024); } while (0)
; #define PG8_MMA(ai, bj, At, Bt) do { __builtin_amdgcn_s_setprio(1); _Pragma("unroll") for (int m = 0; m < 4; ++m) _Pragma("unroll") for (int n = 0; n < 2; ++n) _Pragma("unroll") for (int k = 0; k < 2; ++k) \
;         acc[ai][bj][m][n] = __builtin_amdgcn_mfma_f32_16x16x32_bf16(Bt[n][k], At[m][k], acc[ai][bj][m][n], 0, 0, 0); __builtin_amdgcn_s_setprio(0); } while (0)
; #define PG8_WAIT_V(n) asm volatile("s_waitcnt vmcnt(" #n ")" ::: "memory")
; #define PG8_WAIT_L(n) asm volatile("s_waitcnt lgkmcnt(" #n ")" ::: "memory")
; #define PG8_BAR __builtin_amdgcn_s_barrier()
; #define PG8_SCHED __builtin_amdgcn_sched_barrier(0)
; template <class Epi, bool PERM = true, bool DBLK = false>
; __device__ __forceinline__ void gemm_phase(LAS unsigned char* lds, const Gemm g, const StaticOrder& S, const Epi& E, const int tid) {
;     ...
;             PG8_LDB(B0, 0, 0); PG8_LDB(B1, 0, 1); PG8_SCHED; PG8_LDA(At, 0, 0); PG8_STAGE(PG8_SA(1, 1), a1 + hstep, voffA);
;             PG8_WAIT_V(8); PG8_WAIT_L(0); PG8_BAR; PG8_MMA(0, 0, At, B0); PG8_MMA(0, 1, At, B1); PG8_BAR; PG8_SCHED;
;             PG8_LDA(At, 0, 1); PG8_STAGE(PG8_SB(0, 0), b2, voffB); PG8_STAGE(PG8_SB(0, 1), b2 + hstep, voffB); PG8_STAGE(PG8_SA(0, 0), a2, voffA);
;             PG8_WAIT_V(8); PG8_WAIT_L(0); PG8_BAR; PG8_MMA(1, 0, At, B0); PG8_MMA(1, 1, At, B1); PG8_BAR; PG8_SCHED;
;             PG8_LDB(B0, 1, 0); PG8_LDB(B1, 1, 1); PG8_SCHED; PG8_LDA(At, 1, 0); PG8_STAGE(PG8_SA(0, 1), a2 + hstep, voffA);
;             PG8_WAIT_V(8); PG8_WAIT_L(0); PG8_BAR; PG8_MMA(0, 0, At, B0); PG8_MMA(0, 1, At, B1); PG8_BAR; PG8_SCHED;
.LBB0_212:
	s_add_u32 s34, s74, 0xfffc0080
	s_addc_u32 s35, s75, -1
	s_add_i32 s80, 0, 0x10000
	s_cmp_eq_u32 s83, 12
	s_cselect_b32 vcc_hi, s5, s35
	s_cselect_b32 vcc_lo, s29, s34
	s_cselect_b32 s35, s31, s82
	s_cselect_b32 s34, s55, s92
	s_add_i32 s64, 0, 0x14000
	v_add_u32_e32 v142, s80, v163
	v_add_u32_e32 v162, s64, v163
	ds_read_b128 v[130:133], v142
	ds_read_b128 v[134:137], v142 offset:1024
	ds_read_b128 v[138:141], v142 offset:2048
	ds_read_b128 v[142:145], v142 offset:3072
	ds_read_b128 v[158:161], v162
	ds_read_b128 v[166:169], v162 offset:1024
	ds_read_b128 v[170:173], v162 offset:2048
	ds_read_b128 v[174:177], v162 offset:3072
	v_lshl_add_u64 v[194:195], s[74:75], 0, v[154:155]
	s_add_i32 m0, s21, 0xc000
	ds_read_b128 v[178:181], v165
	ds_read_b128 v[182:185], v165 offset:1024
	ds_read_b128 v[186:189], v165 offset:2048
	ds_read_b128 v[190:193], v165 offset:3072
	ds_read_b128 v[202:205], v165 offset:4096
	ds_read_b128 v[206:209], v165 offset:5120
	ds_read_b128 v[210:213], v165 offset:6144
	ds_read_b128 v[214:217], v165 offset:7168
	global_load_lds_dwordx4 v[194:195], off
	v_lshl_add_u64 v[194:195], s[74:75], 0, v[152:153]
	s_add_i32 m0, s21, 0xe000
	s_nop 0
	global_load_lds_dwordx4 v[194:195], off
	s_waitcnt vmcnt(8)
	s_waitcnt lgkmcnt(0)
	s_barrier
	s_waitcnt lgkmcnt(0)
	v_mfma_f32_16x16x32_bf16 v[126:129], v[130:133], v[178:181], v[126:129]
	v_mfma_f32_16x16x32_bf16 v[122:125], v[138:141], v[178:181], v[122:125]
	v_mfma_f32_16x16x32_bf16 v[118:121], v[130:133], v[186:189], v[118:121]
	v_mfma_f32_16x16x32_bf16 v[110:113], v[138:141], v[186:189], v[110:113]
	v_mfma_f32_16x16x32_bf16 v[102:105], v[130:133], v[202:205], v[102:105]
	v_mfma_f32_16x16x32_bf16 v[94:97], v[138:141], v[202:205], v[94:97]
	v_mfma_f32_16x16x32_bf16 v[86:89], v[130:133], v[210:213], v[86:89]
	v_mfma_f32_16x16x32_bf16 v[78:81], v[138:141], v[210:213], v[78:81]
	v_mfma_f32_16x16x32_bf16 v[126:129], v[134:137], v[182:185], v[126:129]
	v_mfma_f32_16x16x32_bf16 v[122:125], v[142:145], v[182:185], v[122:125]
	v_mfma_f32_16x16x32_bf16 v[118:121], v[134:137], v[190:193], v[118:121]
	v_mfma_f32_16x16x32_bf16 v[110:113], v[142:145], v[190:193], v[110:113]
	v_mfma_f32_16x16x32_bf16 v[102:105], v[134:137], v[206:209], v[102:105]
	v_mfma_f32_16x16x32_bf16 v[94:97], v[142:145], v[206:209], v[94:97]
	v_mfma_f32_16x16x32_bf16 v[86:89], v[134:137], v[214:217], v[86:89]
	v_mfma_f32_16x16x32_bf16 v[78:81], v[142:145], v[214:217], v[78:81]
	v_mfma_f32_16x16x32_bf16 v[114:117], v[158:161], v[178:181], v[114:117]
	v_mfma_f32_16x16x32_bf16 v[106:109], v[170:173], v[178:181], v[106:109]
	v_mfma_f32_16x16x32_bf16 v[98:101], v[158:161], v[186:189], v[98:101]
	v_mfma_f32_16x16x32_bf16 v[90:93], v[170:173], v[186:189], v[90:93]
	v_mfma_f32_16x16x32_bf16 v[82:85], v[158:161], v[202:205], v[82:85]
	v_mfma_f32_16x16x32_bf16 v[74:77], v[170:173], v[202:205], v[74:77]
	v_mfma_f32_16x16x32_bf16 v[70:73], v[158:161], v[210:213], v[70:73]
	v_mfma_f32_16x16x32_bf16 v[66:69], v[170:173], v[210:213], v[66:69]
	v_mfma_f32_16x16x32_bf16 v[114:117], v[166:169], v[182:185], v[114:117]
	v_mfma_f32_16x16x32_bf16 v[106:109], v[174:177], v[182:185], v[106:109]
	v_mfma_f32_16x16x32_bf16 v[98:101], v[166:169], v[190:193], v[98:101]
	v_mfma_f32_16x16x32_bf16 v[90:93], v[174:177], v[190:193], v[90:93]
	v_mfma_f32_16x16x32_bf16 v[82:85], v[166:169], v[206:209], v[82:85]
	v_mfma_f32_16x16x32_bf16 v[74:77], v[174:177], v[206:209], v[74:77]
	v_mfma_f32_16x16x32_bf16 v[70:73], v[166:169], v[214:217], v[70:73]
	v_mfma_f32_16x16x32_bf16 v[66:69], v[174:177], v[214:217], v[66:69]
	s_barrier
	s_add_i32 s80, s80, s20
	v_lshl_add_u64 v[194:195], s[34:35], 0, v[0:1]
	s_mov_b32 m0, s80
	ds_read_b128 v[178:181], v165 offset:16384
	ds_read_b128 v[182:185], v165 offset:17408
	ds_read_b128 v[186:189], v165 offset:18432
	ds_read_b128 v[190:193], v165 offset:19456
	ds_read_b128 v[202:205], v165 offset:20480
	ds_read_b128 v[206:209], v165 offset:21504
	ds_read_b128 v[210:213], v165 offset:22528
	ds_read_b128 v[214:217], v165 offset:23552
	global_load_lds_dwordx4 v[194:195], off
	s_add_i32 m0, s80, 0x2000
	s_add_u32 s80, s34, 0x40000
	v_lshl_add_u64 v[196:197], s[34:35], 0, v[150:151]
	s_addc_u32 s81, s35, 0
	s_add_i32 s64, s64, s20
	global_load_lds_dwordx4 v[196:197], off
	v_lshl_add_u64 v[198:199], s[80:81], 0, v[0:1]
	s_mov_b32 m0, s64
	v_lshl_add_u64 v[200:201], vcc, 0, v[148:149]
	global_load_lds_dwordx4 v[198:199], off
	v_lshl_add_u64 v[198:199], s[80:81], 0, v[150:151]
	s_add_i32 m0, s64, 0x2000
	s_nop 0
	global_load_lds_dwordx4 v[198:199], off
	v_lshl_add_u64 v[198:199], vcc, 0, v[146:147]
	s_mov_b32 m0, s21
	s_nop 0
	global_load_lds_dwordx4 v[198:199], off
	s_mov_b32 m0, s56
	s_nop 0
	global_load_lds_dwordx4 v[200:201], off
	s_waitcnt vmcnt(8)
	s_waitcnt lgkmcnt(0)
	s_barrier
; #define PG8_STAGE(bufoff, gbase, voff) do { _Pragma("unroll") for (int _i = 0; _i < 2; ++_i) \
;         __builtin_amdgcn_global_load_lds((const unsigned*)((const char*)(gbase) + (voff)[_i]), (LAS unsigned*)(lds + (bufoff) + ldsw + _i * 8192), 16, 0, 0); } while (0)
; #define PG8_LDA(dst, b, h) do { _Pragma("unroll") for (int m = 0; m < 4; ++m) _Pragma("unroll") for (int k = 0; k < 2; ++k) dst[m][k] = *(const LAS bf16x8*)(lds + PG8_SA(b, h) + aoff + m * 2048 + k * 1024); } while (0)
; #define PG8_LDB(dst, b, h) do { _Pragma("unroll") for (int n = 0; n < 2; ++n) _Pragma("unroll") for (int k = 0; k < 2; ++k) dst[n][k] = *(const LAS bf16x8*)(lds + PG8_SB(b, h) + boff + n * 2048 + k * 1024); } while (0)
; #define PG8_MMA(ai, bj, At, Bt) do { __builtin_amdgcn_s_setprio(1); _Pragma("unroll") for (int m = 0; m < 4; ++m) _Pragma("unroll") for (int n = 0; n < 2; ++n) _Pragma("unroll") for (int k = 0; k < 2; ++k) \
;         acc[ai][bj][m][n] = __builtin_amdgcn_mfma_f32_16x16x32_bf16(Bt[n][k], At[m][k], acc[ai][bj][m][n], 0, 0, 0); __builtin_amdgcn_s_setprio(0); } while (0)
; #define PG8_WAIT_V(n) asm volatile("s_waitcnt vmcnt(" #n ")" ::: "memory")
; template <class Epi, bool PERM = true, bool DBLK = false>
; __device__ __forceinline__ void gemm_phase(LAS unsigned char* lds, const Gemm g, const StaticOrder& S, const Epi& E, const int tid) {
;     ...
;             PG8_LDB(B0, 0, 0); PG8_LDB(B1, 0, 1); PG8_SCHED; PG8_LDA(At, 0, 0); PG8_STAGE(PG8_SA(1, 1), a1 + hstep, voffA);
;             PG8_WAIT_V(8); PG8_WAIT_L(0); PG8_BAR; PG8_MMA(0, 0, At, B0); PG8_MMA(0, 1, At, B1); PG8_BAR; PG8_SCHED;
;             PG8_LDA(At, 0, 1); PG8_STAGE(PG8_SB(0, 0), b2, voffB); PG8_STAGE(PG8_SB(0, 1), b2 + hstep, voffB); PG8_STAGE(PG8_SA(0, 0), a2, voffA);
;             PG8_WAIT_V(8); PG8_WAIT_L(0); PG8_BAR; PG8_MMA(1, 0, At, B0); PG8_MMA(1, 1, At, B1); PG8_BAR; PG8_SCHED;
;             PG8_LDB(B0, 1, 0); PG8_LDB(B1, 1, 1); PG8_SCHED; PG8_LDA(At, 1, 0); PG8_STAGE(PG8_SA(0, 1), a2 + hstep, voffA);
;             PG8_WAIT_V(8); PG8_WAIT_L(0); PG8_BAR; PG8_MMA(0, 0, At, B0); PG8_MMA(0, 1, At, B1); PG8_BAR; PG8_SCHED;
;             PG8_LDA(At, 1, 1); PG8_STAGE(PG8_SB(1, 0), b3, voffB); PG8_STAGE(PG8_SB(1, 1), b3 + hstep, voffB); PG8_STAGE(PG8_SA(1, 0), a3, voffA);
;             PG8_WAIT_V(8); PG8_WAIT_L(0); PG8_BAR; PG8_MMA(1, 0, At, B0); PG8_MMA(1, 1, At, B1); PG8_BAR; PG8_SCHED;
	s_waitcnt lgkmcnt(0)
	v_mfma_f32_16x16x32_bf16 v[62:65], v[130:133], v[178:181], v[62:65]
	v_mfma_f32_16x16x32_bf16 v[58:61], v[138:141], v[178:181], v[58:61]
	v_mfma_f32_16x16x32_bf16 v[54:57], v[130:133], v[186:189], v[54:57]
	v_mfma_f32_16x16x32_bf16 v[46:49], v[138:141], v[186:189], v[46:49]
	v_mfma_f32_16x16x32_bf16 v[38:41], v[130:133], v[202:205], v[38:41]
	v_mfma_f32_16x16x32_bf16 v[30:33], v[138:141], v[202:205], v[30:33]
	v_mfma_f32_16x16x32_bf16 v[22:25], v[130:133], v[210:213], v[22:25]
	v_mfma_f32_16x16x32_bf16 v[14:17], v[138:141], v[210:213], v[14:17]
	v_mfma_f32_16x16x32_bf16 v[62:65], v[134:137], v[182:185], v[62:65]
	v_mfma_f32_16x16x32_bf16 v[58:61], v[142:145], v[182:185], v[58:61]
	v_mfma_f32_16x16x32_bf16 v[54:57], v[134:137], v[190:193], v[54:57]
	v_mfma_f32_16x16x32_bf16 v[46:49], v[142:145], v[190:193], v[46:49]
	v_mfma_f32_16x16x32_bf16 v[38:41], v[134:137], v[206:209], v[38:41]
	v_mfma_f32_16x16x32_bf16 v[30:33], v[142:145], v[206:209], v[30:33]
	v_mfma_f32_16x16x32_bf16 v[22:25], v[134:137], v[214:217], v[22:25]
	v_mfma_f32_16x16x32_bf16 v[14:17], v[142:145], v[214:217], v[14:17]
	v_mfma_f32_16x16x32_bf16 v[50:53], v[158:161], v[178:181], v[50:53]
	v_mfma_f32_16x16x32_bf16 v[42:45], v[170:173], v[178:181], v[42:45]
	v_mfma_f32_16x16x32_bf16 v[34:37], v[158:161], v[186:189], v[34:37]
	v_mfma_f32_16x16x32_bf16 v[26:29], v[170:173], v[186:189], v[26:29]
	v_mfma_f32_16x16x32_bf16 v[18:21], v[158:161], v[202:205], v[18:21]
	v_mfma_f32_16x16x32_bf16 v[10:13], v[170:173], v[202:205], v[10:13]
	v_mfma_f32_16x16x32_bf16 v[6:9], v[158:161], v[210:213], v[6:9]
	v_mfma_f32_16x16x32_bf16 v[2:5], v[170:173], v[210:213], v[2:5]
	v_mfma_f32_16x16x32_bf16 v[50:53], v[166:169], v[182:185], v[50:53]
	v_mfma_f32_16x16x32_bf16 v[42:45], v[174:177], v[182:185], v[42:45]
	v_mfma_f32_16x16x32_bf16 v[34:37], v[166:169], v[190:193], v[34:37]
	v_mfma_f32_16x16x32_bf16 v[26:29], v[174:177], v[190:193], v[26:29]
	v_mfma_f32_16x16x32_bf16 v[18:21], v[166:169], v[206:209], v[18:21]
	v_mfma_f32_16x16x32_bf16 v[10:13], v[174:177], v[206:209], v[10:13]
	v_mfma_f32_16x16x32_bf16 v[6:9], v[166:169], v[214:217], v[6:9]
	v_mfma_f32_16x16x32_bf16 v[2:5], v[174:177], v[214:217], v[2:5]
	s_barrier
	s_add_i32 s64, 0, 0x18000
	s_add_i32 s96, 0, 0x1c000
	v_add_u32_e32 v142, s64, v163
	v_add_u32_e32 v162, s96, v163
	ds_read_b128 v[130:133], v142
	ds_read_b128 v[134:137], v142 offset:1024
	ds_read_b128 v[138:141], v142 offset:2048
	ds_read_b128 v[142:145], v142 offset:3072
	ds_read_b128 v[158:161], v162
	ds_read_b128 v[166:169], v162 offset:1024
	ds_read_b128 v[170:173], v162 offset:2048
	ds_read_b128 v[174:177], v162 offset:3072
	s_add_u32 s80, vcc_lo, 0x40000
	s_addc_u32 s81, vcc_hi, 0
	s_mov_b32 m0, s57
	v_lshl_add_u64 v[218:219], s[80:81], 0, v[146:147]
	ds_read_b128 v[178:181], v165 offset:32768
	ds_read_b128 v[182:185], v165 offset:33792
	ds_read_b128 v[186:189], v165 offset:34816
	ds_read_b128 v[190:193], v165 offset:35840
	ds_read_b128 v[202:205], v165 offset:36864
	ds_read_b128 v[206:209], v165 offset:37888
	ds_read_b128 v[210:213], v165 offset:38912
	ds_read_b128 v[214:217], v165 offset:39936
	global_load_lds_dwordx4 v[218:219], off
	v_lshl_add_u64 v[218:219], s[80:81], 0, v[148:149]
	s_mov_b32 m0, s59
	s_nop 0
	global_load_lds_dwordx4 v[218:219], off
	s_waitcnt vmcnt(8)
	s_waitcnt lgkmcnt(0)
	s_barrier
	s_waitcnt lgkmcnt(0)
	v_mfma_f32_16x16x32_bf16 v[126:129], v[130:133], v[178:181], v[126:129]
	v_mfma_f32_16x16x32_bf16 v[122:125], v[138:141], v[178:181], v[122:125]
	v_mfma_f32_16x16x32_bf16 v[118:121], v[130:133], v[186:189], v[118:121]
	v_mfma_f32_16x16x32_bf16 v[110:113], v[138:141], v[186:189], v[110:113]
	v_mfma_f32_16x16x32_bf16 v[102:105], v[130:133], v[202:205], v[102:105]
	v_mfma_f32_16x16x32_bf16 v[94:97], v[138:141], v[202:205], v[94:97]
	v_mfma_f32_16x16x32_bf16 v[86:89], v[130:133], v[210:213], v[86:89]
	v_mfma_f32_16x16x32_bf16 v[78:81], v[138:141], v[210:213], v[78:81]
	v_mfma_f32_16x16x32_bf16 v[126:129], v[134:137], v[182:185], v[126:129]
	v_mfma_f32_16x16x32_bf16 v[122:125], v[142:145], v[182:185], v[122:125]
	v_mfma_f32_16x16x32_bf16 v[118:121], v[134:137], v[190:193], v[118:121]
	v_mfma_f32_16x16x32_bf16 v[110:113], v[142:145], v[190:193], v[110:113]
	v_mfma_f32_16x16x32_bf16 v[102:105], v[134:137], v[206:209], v[102:105]
	v_mfma_f32_16x16x32_bf16 v[94:97], v[142:145], v[206:209], v[94:97]
	v_mfma_f32_16x16x32_bf16 v[86:89], v[134:137], v[214:217], v[86:89]
	v_mfma_f32_16x16x32_bf16 v[78:81], v[142:145], v[214:217], v[78:81]
	v_mfma_f32_16x16x32_bf16 v[114:117], v[158:161], v[178:181], v[114:117]
	v_mfma_f32_16x16x32_bf16 v[106:109], v[170:173], v[178:181], v[106:109]
	v_mfma_f32_16x16x32_bf16 v[98:101], v[158:161], v[186:189], v[98:101]
	v_mfma_f32_16x16x32_bf16 v[90:93], v[170:173], v[186:189], v[90:93]
	v_mfma_f32_16x16x32_bf16 v[82:85], v[158:161], v[202:205], v[82:85]
	v_mfma_f32_16x16x32_bf16 v[74:77], v[170:173], v[202:205], v[74:77]
	v_mfma_f32_16x16x32_bf16 v[70:73], v[158:161], v[210:213], v[70:73]
	v_mfma_f32_16x16x32_bf16 v[66:69], v[170:173], v[210:213], v[66:69]
	v_mfma_f32_16x16x32_bf16 v[114:117], v[166:169], v[182:185], v[114:117]
	v_mfma_f32_16x16x32_bf16 v[106:109], v[174:177], v[182:185], v[106:109]
	v_mfma_f32_16x16x32_bf16 v[98:101], v[166:169], v[190:193], v[98:101]
	v_mfma_f32_16x16x32_bf16 v[90:93], v[174:177], v[190:193], v[90:93]
	v_mfma_f32_16x16x32_bf16 v[82:85], v[166:169], v[206:209], v[82:85]
	v_mfma_f32_16x16x32_bf16 v[74:77], v[174:177], v[206:209], v[74:77]
	v_mfma_f32_16x16x32_bf16 v[70:73], v[166:169], v[214:217], v[70:73]
	v_mfma_f32_16x16x32_bf16 v[66:69], v[174:177], v[214:217], v[66:69]
	s_barrier
; #define PG8_STAGE(bufoff, gbase, voff) do { _Pragma("unroll") for (int _i = 0; _i < 2; ++_i) \
;         __builtin_amdgcn_global_load_lds((const unsigned*)((const char*)(gbase) + (voff)[_i]), (LAS unsigned*)(lds + (bufoff) + ldsw + _i * 8192), 16, 0, 0); } while (0)
; #define PG8_LDA(dst, b, h) do { _Pragma("unroll") for (int m = 0; m < 4; ++m) _Pragma("unroll") for (int k = 0; k < 2; ++k) dst[m][k] = *(const LAS bf16x8*)(lds + PG8_SA(b, h) + aoff + m * 2048 + k * 1024); } while (0)
; #define PG8_LDB(dst, b, h) do { _Pragma("unroll") for (int n = 0; n < 2; ++n) _Pragma("unroll") for (int k = 0; k < 2; ++k) dst[n][k] = *(const LAS bf16x8*)(lds + PG8_SB(b, h) + boff + n * 2048 + k * 1024); } while (0)
; #define PG8_MMA(ai, bj, At, Bt) do { __builtin_amdgcn_s_setprio(1); _Pragma("unroll") for (int m = 0; m < 4; ++m) _Pragma("unroll") for (int n = 0; n < 2; ++n) _Pragma("unroll") for (int k = 0; k < 2; ++k) \
;         acc[ai][bj][m][n] = __builtin_amdgcn_mfma_f32_16x16x32_bf16(Bt[n][k], At[m][k], acc[ai][bj][m][n], 0, 0, 0); __builtin_amdgcn_s_setprio(0); } while (0)
; #define PG8_WAIT_V(n) asm volatile("s_waitcnt vmcnt(" #n ")" ::: "memory")
; #define PG8_WAIT_L(n) asm volatile("s_waitcnt lgkmcnt(" #n ")" ::: "memory")
; #define PG8_BAR __builtin_amdgcn_s_barrier()
; #define PG8_SCHED __builtin_amdgcn_sched_barrier(0)
; template <class Epi, bool PERM = true, bool DBLK = false>
; __device__ __forceinline__ void gemm_phase(LAS unsigned char* lds, const Gemm g, const StaticOrder& S, const Epi& E, const int tid) {
;     ...
;             PG8_LDB(B0, 1, 0); PG8_LDB(B1, 1, 1); PG8_SCHED; PG8_LDA(At, 1, 0); PG8_STAGE(PG8_SA(0, 1), a2 + hstep, voffA);
;             PG8_WAIT_V(8); PG8_WAIT_L(0); PG8_BAR; PG8_MMA(0, 0, At, B0); PG8_MMA(0, 1, At, B1); PG8_BAR; PG8_SCHED;
;             PG8_LDA(At, 1, 1); PG8_STAGE(PG8_SB(1, 0), b3, voffB); PG8_STAGE(PG8_SB(1, 1), b3 + hstep, voffB); PG8_STAGE(PG8_SA(1, 0), a3, voffA);
;             PG8_WAIT_V(8); PG8_WAIT_L(0); PG8_BAR; PG8_MMA(1, 0, At, B0); PG8_MMA(1, 1, At, B1); PG8_BAR; PG8_SCHED;
;         }
	s_add_i32 s64, s64, s20
	v_lshl_add_u64 v[194:195], v[194:195], 0, s[84:85]
	s_mov_b32 m0, s64
	ds_read_b128 v[178:181], v165 offset:49152
	ds_read_b128 v[182:185], v165 offset:50176
	ds_read_b128 v[186:189], v165 offset:51200
	ds_read_b128 v[190:193], v165 offset:52224
	ds_read_b128 v[202:205], v165 offset:53248
	ds_read_b128 v[206:209], v165 offset:54272
	ds_read_b128 v[210:213], v165 offset:55296
	ds_read_b128 v[214:217], v165 offset:56320
	global_load_lds_dwordx4 v[194:195], off
	s_add_i32 m0, s64, 0x2000
	s_add_u32 s34, s34, 0x40080
	v_lshl_add_u64 v[194:195], v[196:197], 0, s[84:85]
	s_addc_u32 s35, s35, 0
	s_add_i32 s64, s96, s20
	global_load_lds_dwordx4 v[194:195], off
	v_lshl_add_u64 v[194:195], s[34:35], 0, v[0:1]
	s_mov_b32 m0, s64
	s_nop 0
	global_load_lds_dwordx4 v[194:195], off
	v_lshl_add_u64 v[194:195], s[34:35], 0, v[150:151]
	s_add_i32 m0, s64, 0x2000
	s_nop 0
	global_load_lds_dwordx4 v[194:195], off
	v_lshl_add_u64 v[194:195], v[198:199], 0, s[84:85]
	s_mov_b32 m0, s62
	s_nop 0
	global_load_lds_dwordx4 v[194:195], off
	v_lshl_add_u64 v[194:195], v[200:201], 0, s[84:85]
	s_mov_b32 m0, s63
	s_nop 0
	global_load_lds_dwordx4 v[194:195], off
	s_waitcnt vmcnt(8)
	s_waitcnt lgkmcnt(0)
	s_barrier
	s_waitcnt lgkmcnt(0)
	v_mfma_f32_16x16x32_bf16 v[62:65], v[130:133], v[178:181], v[62:65]
	v_mfma_f32_16x16x32_bf16 v[58:61], v[138:141], v[178:181], v[58:61]
	v_mfma_f32_16x16x32_bf16 v[54:57], v[130:133], v[186:189], v[54:57]
	v_mfma_f32_16x16x32_bf16 v[46:49], v[138:141], v[186:189], v[46:49]
	v_mfma_f32_16x16x32_bf16 v[38:41], v[130:133], v[202:205], v[38:41]
	v_mfma_f32_16x16x32_bf16 v[30:33], v[138:141], v[202:205], v[30:33]
	v_mfma_f32_16x16x32_bf16 v[22:25], v[130:133], v[210:213], v[22:25]
	v_mfma_f32_16x16x32_bf16 v[14:17], v[138:141], v[210:213], v[14:17]
	v_mfma_f32_16x16x32_bf16 v[62:65], v[134:137], v[182:185], v[62:65]
	v_mfma_f32_16x16x32_bf16 v[58:61], v[142:145], v[182:185], v[58:61]
	v_mfma_f32_16x16x32_bf16 v[54:57], v[134:137], v[190:193], v[54:57]
	v_mfma_f32_16x16x32_bf16 v[46:49], v[142:145], v[190:193], v[46:49]
	v_mfma_f32_16x16x32_bf16 v[38:41], v[134:137], v[206:209], v[38:41]
	v_mfma_f32_16x16x32_bf16 v[30:33], v[142:145], v[206:209], v[30:33]
	v_mfma_f32_16x16x32_bf16 v[22:25], v[134:137], v[214:217], v[22:25]
	v_mfma_f32_16x16x32_bf16 v[14:17], v[142:145], v[214:217], v[14:17]
	v_mfma_f32_16x16x32_bf16 v[50:53], v[158:161], v[178:181], v[50:53]
	v_mfma_f32_16x16x32_bf16 v[42:45], v[170:173], v[178:181], v[42:45]
	v_mfma_f32_16x16x32_bf16 v[34:37], v[158:161], v[186:189], v[34:37]
	v_mfma_f32_16x16x32_bf16 v[26:29], v[170:173], v[186:189], v[26:29]
	v_mfma_f32_16x16x32_bf16 v[18:21], v[158:161], v[202:205], v[18:21]
	v_mfma_f32_16x16x32_bf16 v[10:13], v[170:173], v[202:205], v[10:13]
	v_mfma_f32_16x16x32_bf16 v[6:9], v[158:161], v[210:213], v[6:9]
	v_mfma_f32_16x16x32_bf16 v[2:5], v[170:173], v[210:213], v[2:5]
	v_mfma_f32_16x16x32_bf16 v[50:53], v[166:169], v[182:185], v[50:53]
	v_mfma_f32_16x16x32_bf16 v[42:45], v[174:177], v[182:185], v[42:45]
	v_mfma_f32_16x16x32_bf16 v[34:37], v[166:169], v[190:193], v[34:37]
	v_mfma_f32_16x16x32_bf16 v[26:29], v[174:177], v[190:193], v[26:29]
	v_mfma_f32_16x16x32_bf16 v[18:21], v[166:169], v[206:209], v[18:21]
	v_mfma_f32_16x16x32_bf16 v[10:13], v[174:177], v[206:209], v[10:13]
	v_mfma_f32_16x16x32_bf16 v[6:9], v[166:169], v[214:217], v[6:9]
	v_mfma_f32_16x16x32_bf16 v[2:5], v[174:177], v[214:217], v[2:5]
	s_barrier
	s_add_i32 s83, s83, 2
	s_add_u32 s92, s92, 0x100
	s_addc_u32 s82, s82, 0
	s_add_u32 s74, s74, 0x100
	s_addc_u32 s75, s75, 0
	s_cmp_gt_u32 s83, 13
	s_cbranch_scc0 .LBB0_212
	s_and_b64 vcc, exec, s[26:27]
	s_cbranch_vccz .LBB0_215
	s_barrier

; #define PG8_STAGE(bufoff, gbase, voff) do { _Pragma("unroll") for (int _i = 0; _i < 2; ++_i) \
;         __builtin_amdgcn_global_load_lds((const unsigned*)((const char*)(gbase) + (voff)[_i]), (LAS unsigned*)(lds + (bufoff) + ldsw + _i * 8192), 16, 0, 0); } while (0)
; #define PG8_LDA(dst, b, h) do { _Pragma("unroll") for (int m = 0; m < 4; ++m) _Pragma("unroll") for (int k = 0; k < 2; ++k) dst[m][k] = *(const LAS bf16x8*)(lds + PG8_SA(b, h) + aoff + m * 2048 + k * 1024); } while (0)
; #define PG8_LDB(dst, b, h) do { _Pragma("unroll") for (int n = 0; n < 2; ++n) _Pragma("unroll") for (int k = 0; k < 2; ++k) dst[n][k] = *(const LAS bf16x8*)(lds + PG8_SB(b, h) + boff + n * 2048 + k * 1024); } while (0)
; #define PG8_WAIT_V(n) asm volatile("s_waitcnt vmcnt(" #n ")" ::: "memory")
; #define PG8_WAIT_L(n) asm volatile("s_waitcnt lgkmcnt(" #n ")" ::: "memory")
; #define PG8_BAR __builtin_amdgcn_s_barrier()
; template <class Epi, bool PERM = true, bool DBLK = false>
; __device__ __forceinline__ void gemm_phase(LAS unsigned char* lds, const Gemm g, const StaticOrder& S, const Epi& E, const int tid) {
;     ...
;         const bool has_next = S.next(ui + 1, nxt);
;         const char* nA = has_next ? (const char*)g.A + (size_t)nxt.pm * tstep : cA; const char* nB = has_next ? (const char*)g.Bt + (size_t)nxt.pn * tstep : cB;
;         for (int t2 = 0; t2 < (DBLK ? 2 * nt : nt); t2 += 2) {
;             const int t = DBLK ? (t2 >= nt ? t2 - nt : t2) : t2;
;             const bool lastp = (t == nt - 2);
;             const bool last = DBLK ? (t2 == 2 * nt - 2) : lastp;
;             const char* a1 = cA + (size_t)(t + 1) * kstep;
;             const char* a2 = last ? nA : (lastp ? cA : cA + (size_t)(t + 2) * kstep); const char* b2 = last ? nB : (lastp ? cB : cB + (size_t)(t + 2) * kstep);
;             const char* a3 = a2 + kstep; const char* b3 = b2 + kstep;
;             PG8_LDB(B0, 0, 0); PG8_LDB(B1, 0, 1); PG8_SCHED; PG8_LDA(At, 0, 0); PG8_STAGE(PG8_SA(1, 1), a1 + hstep, voffA);
;             PG8_WAIT_V(8); PG8_WAIT_L(0); PG8_BAR; PG8_MMA(0, 0, At, B0); PG8_MMA(0, 1, At, B1); PG8_BAR; PG8_SCHED;
;             PG8_LDA(At, 0, 1); PG8_STAGE(PG8_SB(0, 0), b2, voffB); PG8_STAGE(PG8_SB(0, 1), b2 + hstep, voffB); PG8_STAGE(PG8_SA(0, 0), a2, voffA);
;             PG8_WAIT_V(8); PG8_WAIT_L(0); PG8_BAR; PG8_MMA(1, 0, At, B0); PG8_MMA(1, 1, At, B1); PG8_BAR; PG8_SCHED;
.LBB0_298:
	s_ashr_i32 s15, s14, 31
	s_lshl_b64 s[16:17], s[14:15], 17
	s_add_u32 s16, s2, s16
	s_addc_u32 s17, s3, s17
	s_and_b64 s[18:19], s[0:1], exec
	s_cselect_b32 s31, s17, s23
	s_cselect_b32 s30, s16, s22
	s_ashr_i32 s13, s12, 31
	s_lshl_b64 s[18:19], s[12:13], 17
	s_add_u32 s18, s20, s18
	s_addc_u32 s19, s21, s19
	s_and_b64 s[26:27], s[0:1], exec
	s_cselect_b32 s27, s19, s29
	s_cselect_b32 s26, s18, s28
	s_add_i32 s72, 0, 0x10000
	s_add_i32 s64, 0, 0x14000
	v_add_u32_e32 v212, s72, v136
	v_add_u32_e32 v213, s64, v136
	ds_read_b128 v[2:5], v212
	ds_read_b128 v[6:9], v212 offset:1024
	ds_read_b128 v[10:13], v212 offset:2048
	ds_read_b128 v[14:17], v212 offset:3072
	s_waitcnt vmcnt(0)
	ds_read_b128 v[18:21], v213
	ds_read_b128 v[22:25], v213 offset:1024
	ds_read_b128 v[26:29], v213 offset:2048
	ds_read_b128 v[30:33], v213 offset:3072
	s_add_u32 s66, s22, 0x10080
	s_addc_u32 s67, s23, 0
	s_add_i32 s74, s35, 0xc000
	v_lshl_add_u64 v[66:67], s[66:67], 0, v[134:135]
	s_mov_b32 m0, s74
	s_add_i32 s13, s35, 0xe000
	ds_read_b128 v[34:37], v137
	ds_read_b128 v[38:41], v137 offset:1024
	ds_read_b128 v[42:45], v137 offset:2048
	ds_read_b128 v[46:49], v137 offset:3072
	ds_read_b128 v[50:53], v137 offset:4096
	ds_read_b128 v[54:57], v137 offset:5120
	ds_read_b128 v[58:61], v137 offset:6144
	ds_read_b128 v[62:65], v137 offset:7168
	global_load_lds_dwordx4 v[66:67], off
	v_lshl_add_u64 v[66:67], s[66:67], 0, v[132:133]
	s_mov_b32 m0, s13
	s_nop 0
	global_load_lds_dwordx4 v[66:67], off
	s_waitcnt vmcnt(8)
	s_waitcnt lgkmcnt(0)
	s_barrier
	s_waitcnt lgkmcnt(0)
	v_mfma_f32_16x16x32_bf16 v[66:69], v[2:5], v[34:37], 0
	v_mfma_f32_16x16x32_bf16 v[70:73], v[10:13], v[34:37], 0
	v_mfma_f32_16x16x32_bf16 v[74:77], v[2:5], v[42:45], 0
	v_mfma_f32_16x16x32_bf16 v[78:81], v[10:13], v[42:45], 0
	v_mfma_f32_16x16x32_bf16 v[82:85], v[2:5], v[50:53], 0
	v_mfma_f32_16x16x32_bf16 v[86:89], v[10:13], v[50:53], 0
	v_mfma_f32_16x16x32_bf16 v[90:93], v[2:5], v[58:61], 0
	v_mfma_f32_16x16x32_bf16 v[94:97], v[10:13], v[58:61], 0
	v_mfma_f32_16x16x32_bf16 v[66:69], v[6:9], v[38:41], v[66:69]
	v_mfma_f32_16x16x32_bf16 v[70:73], v[14:17], v[38:41], v[70:73]
	v_mfma_f32_16x16x32_bf16 v[74:77], v[6:9], v[46:49], v[74:77]
	v_mfma_f32_16x16x32_bf16 v[78:81], v[14:17], v[46:49], v[78:81]
	v_mfma_f32_16x16x32_bf16 v[82:85], v[6:9], v[54:57], v[82:85]
	v_mfma_f32_16x16x32_bf16 v[86:89], v[14:17], v[54:57], v[86:89]
	v_mfma_f32_16x16x32_bf16 v[90:93], v[6:9], v[62:65], v[90:93]
	v_mfma_f32_16x16x32_bf16 v[94:97], v[14:17], v[62:65], v[94:97]
	v_mfma_f32_16x16x32_bf16 v[98:101], v[18:21], v[34:37], 0
	v_mfma_f32_16x16x32_bf16 v[34:37], v[26:29], v[34:37], 0
	v_mfma_f32_16x16x32_bf16 v[98:101], v[22:25], v[38:41], v[98:101]
	v_mfma_f32_16x16x32_bf16 v[34:37], v[30:33], v[38:41], v[34:37]
	v_mfma_f32_16x16x32_bf16 v[38:41], v[18:21], v[42:45], 0
	v_mfma_f32_16x16x32_bf16 v[42:45], v[26:29], v[42:45], 0
	v_mfma_f32_16x16x32_bf16 v[38:41], v[22:25], v[46:49], v[38:41]
	v_mfma_f32_16x16x32_bf16 v[42:45], v[30:33], v[46:49], v[42:45]
	v_mfma_f32_16x16x32_bf16 v[46:49], v[18:21], v[50:53], 0
	v_mfma_f32_16x16x32_bf16 v[50:53], v[26:29], v[50:53], 0
	v_mfma_f32_16x16x32_bf16 v[46:49], v[22:25], v[54:57], v[46:49]
	v_mfma_f32_16x16x32_bf16 v[50:53], v[30:33], v[54:57], v[50:53]
	v_mfma_f32_16x16x32_bf16 v[54:57], v[18:21], v[58:61], 0
	v_mfma_f32_16x16x32_bf16 v[58:61], v[26:29], v[58:61], 0
	v_mfma_f32_16x16x32_bf16 v[54:57], v[22:25], v[62:65], v[54:57]
	v_mfma_f32_16x16x32_bf16 v[58:61], v[30:33], v[62:65], v[58:61]
	s_barrier
	s_add_i32 s72, s72, s34
	v_lshl_add_u64 v[194:195], s[28:29], 0, v[0:1]
	s_mov_b64 s[82:83], 0x100
	s_add_i32 s15, s72, 0x2000
	v_lshl_add_u64 v[138:139], v[194:195], 0, s[82:83]
	s_mov_b32 m0, s72
	v_lshl_add_u64 v[196:197], s[28:29], 0, v[130:131]
	s_add_u32 s78, s28, 0x10100
	ds_read_b128 v[62:65], v137 offset:16384
	ds_read_b128 v[102:105], v137 offset:17408
	ds_read_b128 v[106:109], v137 offset:18432
	ds_read_b128 v[110:113], v137 offset:19456
	ds_read_b128 v[114:117], v137 offset:20480
	ds_read_b128 v[118:121], v137 offset:21504
	ds_read_b128 v[122:125], v137 offset:22528
	ds_read_b128 v[126:129], v137 offset:23552
	global_load_lds_dwordx4 v[138:139], off
	v_lshl_add_u64 v[138:139], v[196:197], 0, s[82:83]
	s_mov_b32 m0, s15
	s_addc_u32 s79, s29, 0
	s_add_i32 s66, s64, s34
	global_load_lds_dwordx4 v[138:139], off
	v_lshl_add_u64 v[138:139], s[78:79], 0, v[0:1]
	s_mov_b32 m0, s66
	s_add_i32 s67, s66, 0x2000
	global_load_lds_dwordx4 v[138:139], off
	v_lshl_add_u64 v[138:139], s[78:79], 0, v[130:131]
	s_mov_b32 m0, s67
	v_lshl_add_u64 v[198:199], s[22:23], 0, v[134:135]
	global_load_lds_dwordx4 v[138:139], off
	v_lshl_add_u64 v[138:139], v[198:199], 0, s[82:83]
	s_mov_b32 m0, s35
	v_lshl_add_u64 v[200:201], s[22:23], 0, v[132:133]
	global_load_lds_dwordx4 v[138:139], off
	v_lshl_add_u64 v[138:139], v[200:201], 0, s[82:83]
	s_mov_b32 m0, s36
	s_nop 0
	global_load_lds_dwordx4 v[138:139], off
	s_waitcnt vmcnt(8)
	s_waitcnt lgkmcnt(0)
	s_barrier
; #define PG8_STAGE(bufoff, gbase, voff) do { _Pragma("unroll") for (int _i = 0; _i < 2; ++_i) \
;         __builtin_amdgcn_global_load_lds((const unsigned*)((const char*)(gbase) + (voff)[_i]), (LAS unsigned*)(lds + (bufoff) + ldsw + _i * 8192), 16, 0, 0); } while (0)
; #define PG8_LDA(dst, b, h) do { _Pragma("unroll") for (int m = 0; m < 4; ++m) _Pragma("unroll") for (int k = 0; k < 2; ++k) dst[m][k] = *(const LAS bf16x8*)(lds + PG8_SA(b, h) + aoff + m * 2048 + k * 1024); } while (0)
; #define PG8_LDB(dst, b, h) do { _Pragma("unroll") for (int n = 0; n < 2; ++n) _Pragma("unroll") for (int k = 0; k < 2; ++k) dst[n][k] = *(const LAS bf16x8*)(lds + PG8_SB(b, h) + boff + n * 2048 + k * 1024); } while (0)
; #define PG8_MMA(ai, bj, At, Bt) do { __builtin_amdgcn_s_setprio(1); _Pragma("unroll") for (int m = 0; m < 4; ++m) _Pragma("unroll") for (int n = 0; n < 2; ++n) _Pragma("unroll") for (int k = 0; k < 2; ++k) \
;         acc[ai][bj][m][n] = __builtin_amdgcn_mfma_f32_16x16x32_bf16(Bt[n][k], At[m][k], acc[ai][bj][m][n], 0, 0, 0); __builtin_amdgcn_s_setprio(0); } while (0)
; #define PG8_WAIT_V(n) asm volatile("s_waitcnt vmcnt(" #n ")" ::: "memory")
; #define PG8_WAIT_L(n) asm volatile("s_waitcnt lgkmcnt(" #n ")" ::: "memory")
; #define PG8_BAR __builtin_amdgcn_s_barrier()
; #define PG8_SCHED __builtin_amdgcn_sched_barrier(0)
; template <class Epi, bool PERM = true, bool DBLK = false>
; __device__ __forceinline__ void gemm_phase(LAS unsigned char* lds, const Gemm g, const StaticOrder& S, const Epi& E, const int tid) {
;     ...
;             PG8_WAIT_V(8); PG8_WAIT_L(0); PG8_BAR; PG8_MMA(1, 0, At, B0); PG8_MMA(1, 1, At, B1); PG8_BAR; PG8_SCHED;
;             PG8_LDB(B0, 1, 0); PG8_LDB(B1, 1, 1); PG8_SCHED; PG8_LDA(At, 1, 0); PG8_STAGE(PG8_SA(0, 1), a2 + hstep, voffA);
;             PG8_WAIT_V(8); PG8_WAIT_L(0); PG8_BAR; PG8_MMA(0, 0, At, B0); PG8_MMA(0, 1, At, B1); PG8_BAR; PG8_SCHED;
;             PG8_LDA(At, 1, 1); PG8_STAGE(PG8_SB(1, 0), b3, voffB); PG8_STAGE(PG8_SB(1, 1), b3 + hstep, voffB); PG8_STAGE(PG8_SA(1, 0), a3, voffA);
	s_waitcnt lgkmcnt(0)
	v_mfma_f32_16x16x32_bf16 v[138:141], v[2:5], v[62:65], 0
	v_mfma_f32_16x16x32_bf16 v[146:149], v[2:5], v[106:109], 0
	v_mfma_f32_16x16x32_bf16 v[154:157], v[2:5], v[114:117], 0
	v_mfma_f32_16x16x32_bf16 v[2:5], v[2:5], v[122:125], 0
	v_mfma_f32_16x16x32_bf16 v[138:141], v[6:9], v[102:105], v[138:141]
	v_mfma_f32_16x16x32_bf16 v[146:149], v[6:9], v[110:113], v[146:149]
	v_mfma_f32_16x16x32_bf16 v[154:157], v[6:9], v[118:121], v[154:157]
	v_mfma_f32_16x16x32_bf16 v[2:5], v[6:9], v[126:129], v[2:5]
	v_mfma_f32_16x16x32_bf16 v[6:9], v[10:13], v[122:125], 0
	v_mfma_f32_16x16x32_bf16 v[142:145], v[10:13], v[62:65], 0
	v_mfma_f32_16x16x32_bf16 v[150:153], v[10:13], v[106:109], 0
	v_mfma_f32_16x16x32_bf16 v[158:161], v[10:13], v[114:117], 0
	v_mfma_f32_16x16x32_bf16 v[6:9], v[14:17], v[126:129], v[6:9]
	v_mfma_f32_16x16x32_bf16 v[142:145], v[14:17], v[102:105], v[142:145]
	v_mfma_f32_16x16x32_bf16 v[150:153], v[14:17], v[110:113], v[150:153]
	v_mfma_f32_16x16x32_bf16 v[158:161], v[14:17], v[118:121], v[158:161]
	v_mfma_f32_16x16x32_bf16 v[10:13], v[18:21], v[62:65], 0
	v_mfma_f32_16x16x32_bf16 v[14:17], v[26:29], v[62:65], 0
	v_mfma_f32_16x16x32_bf16 v[10:13], v[22:25], v[102:105], v[10:13]
	v_mfma_f32_16x16x32_bf16 v[14:17], v[30:33], v[102:105], v[14:17]
	v_mfma_f32_16x16x32_bf16 v[62:65], v[18:21], v[106:109], 0
	v_mfma_f32_16x16x32_bf16 v[102:105], v[26:29], v[106:109], 0
	v_mfma_f32_16x16x32_bf16 v[106:109], v[18:21], v[114:117], 0
	v_mfma_f32_16x16x32_bf16 v[18:21], v[18:21], v[122:125], 0
	v_mfma_f32_16x16x32_bf16 v[62:65], v[22:25], v[110:113], v[62:65]
	v_mfma_f32_16x16x32_bf16 v[102:105], v[30:33], v[110:113], v[102:105]
	v_mfma_f32_16x16x32_bf16 v[106:109], v[22:25], v[118:121], v[106:109]
	v_mfma_f32_16x16x32_bf16 v[110:113], v[26:29], v[114:117], 0
	v_mfma_f32_16x16x32_bf16 v[18:21], v[22:25], v[126:129], v[18:21]
	v_mfma_f32_16x16x32_bf16 v[22:25], v[26:29], v[122:125], 0
	v_mfma_f32_16x16x32_bf16 v[110:113], v[30:33], v[118:121], v[110:113]
	v_mfma_f32_16x16x32_bf16 v[22:25], v[30:33], v[126:129], v[22:25]
	s_barrier
	s_add_i32 s75, 0, 0x18000
	s_add_i32 s64, 0, 0x1c000
	v_add_u32_e32 v218, s75, v136
	v_add_u32_e32 v226, s64, v136
	ds_read_b128 v[26:29], v218
	ds_read_b128 v[30:33], v218 offset:1024
	ds_read_b128 v[114:117], v218 offset:2048
	ds_read_b128 v[118:121], v218 offset:3072
	ds_read_b128 v[122:125], v226
	ds_read_b128 v[126:129], v226 offset:1024
	ds_read_b128 v[162:165], v226 offset:2048
	ds_read_b128 v[166:169], v226 offset:3072
	s_add_u32 s78, s22, 0x10100
	s_addc_u32 s79, s23, 0
	s_mov_b32 m0, s52
	v_lshl_add_u64 v[210:211], s[78:79], 0, v[134:135]
	ds_read_b128 v[170:173], v137 offset:32768
	ds_read_b128 v[174:177], v137 offset:33792
	ds_read_b128 v[178:181], v137 offset:34816
	ds_read_b128 v[182:185], v137 offset:35840
	ds_read_b128 v[186:189], v137 offset:36864
	ds_read_b128 v[190:193], v137 offset:37888
	ds_read_b128 v[202:205], v137 offset:38912
	ds_read_b128 v[206:209], v137 offset:39936
	global_load_lds_dwordx4 v[210:211], off
	v_lshl_add_u64 v[210:211], s[78:79], 0, v[132:133]
	s_mov_b32 m0, s53
	s_nop 0
	global_load_lds_dwordx4 v[210:211], off
	s_waitcnt vmcnt(8)
	s_waitcnt lgkmcnt(0)
	s_barrier
	s_waitcnt lgkmcnt(0)
	v_mfma_f32_16x16x32_bf16 v[66:69], v[26:29], v[170:173], v[66:69]
	v_mfma_f32_16x16x32_bf16 v[70:73], v[114:117], v[170:173], v[70:73]
	v_mfma_f32_16x16x32_bf16 v[74:77], v[26:29], v[178:181], v[74:77]
	v_mfma_f32_16x16x32_bf16 v[78:81], v[114:117], v[178:181], v[78:81]
	v_mfma_f32_16x16x32_bf16 v[82:85], v[26:29], v[186:189], v[82:85]
	v_mfma_f32_16x16x32_bf16 v[86:89], v[114:117], v[186:189], v[86:89]
	v_mfma_f32_16x16x32_bf16 v[90:93], v[26:29], v[202:205], v[90:93]
	v_mfma_f32_16x16x32_bf16 v[94:97], v[114:117], v[202:205], v[94:97]
	v_mfma_f32_16x16x32_bf16 v[66:69], v[30:33], v[174:177], v[66:69]
	v_mfma_f32_16x16x32_bf16 v[70:73], v[118:121], v[174:177], v[70:73]
	v_mfma_f32_16x16x32_bf16 v[74:77], v[30:33], v[182:185], v[74:77]
	v_mfma_f32_16x16x32_bf16 v[78:81], v[118:121], v[182:185], v[78:81]
	v_mfma_f32_16x16x32_bf16 v[82:85], v[30:33], v[190:193], v[82:85]
	v_mfma_f32_16x16x32_bf16 v[86:89], v[118:121], v[190:193], v[86:89]
	v_mfma_f32_16x16x32_bf16 v[90:93], v[30:33], v[206:209], v[90:93]
	v_mfma_f32_16x16x32_bf16 v[94:97], v[118:121], v[206:209], v[94:97]
	v_mfma_f32_16x16x32_bf16 v[98:101], v[122:125], v[170:173], v[98:101]
	v_mfma_f32_16x16x32_bf16 v[34:37], v[162:165], v[170:173], v[34:37]
	v_mfma_f32_16x16x32_bf16 v[38:41], v[122:125], v[178:181], v[38:41]
	v_mfma_f32_16x16x32_bf16 v[42:45], v[162:165], v[178:181], v[42:45]
	v_mfma_f32_16x16x32_bf16 v[46:49], v[122:125], v[186:189], v[46:49]
	v_mfma_f32_16x16x32_bf16 v[50:53], v[162:165], v[186:189], v[50:53]
	v_mfma_f32_16x16x32_bf16 v[54:57], v[122:125], v[202:205], v[54:57]
	v_mfma_f32_16x16x32_bf16 v[58:61], v[162:165], v[202:205], v[58:61]
	v_mfma_f32_16x16x32_bf16 v[98:101], v[126:129], v[174:177], v[98:101]
	v_mfma_f32_16x16x32_bf16 v[34:37], v[166:169], v[174:177], v[34:37]
	v_mfma_f32_16x16x32_bf16 v[38:41], v[126:129], v[182:185], v[38:41]
	v_mfma_f32_16x16x32_bf16 v[42:45], v[166:169], v[182:185], v[42:45]
	v_mfma_f32_16x16x32_bf16 v[46:49], v[126:129], v[190:193], v[46:49]
	v_mfma_f32_16x16x32_bf16 v[50:53], v[166:169], v[190:193], v[50:53]
	v_mfma_f32_16x16x32_bf16 v[54:57], v[126:129], v[206:209], v[54:57]
	v_mfma_f32_16x16x32_bf16 v[58:61], v[166:169], v[206:209], v[58:61]
	s_barrier
; #define PG8_STAGE(bufoff, gbase, voff) do { _Pragma("unroll") for (int _i = 0; _i < 2; ++_i) \
;         __builtin_amdgcn_global_load_lds((const unsigned*)((const char*)(gbase) + (voff)[_i]), (LAS unsigned*)(lds + (bufoff) + ldsw + _i * 8192), 16, 0, 0); } while (0)
; #define PG8_LDA(dst, b, h) do { _Pragma("unroll") for (int m = 0; m < 4; ++m) _Pragma("unroll") for (int k = 0; k < 2; ++k) dst[m][k] = *(const LAS bf16x8*)(lds + PG8_SA(b, h) + aoff + m * 2048 + k * 1024); } while (0)
; #define PG8_LDB(dst, b, h) do { _Pragma("unroll") for (int n = 0; n < 2; ++n) _Pragma("unroll") for (int k = 0; k < 2; ++k) dst[n][k] = *(const LAS bf16x8*)(lds + PG8_SB(b, h) + boff + n * 2048 + k * 1024); } while (0)
; #define PG8_MMA(ai, bj, At, Bt) do { __builtin_amdgcn_s_setprio(1); _Pragma("unroll") for (int m = 0; m < 4; ++m) _Pragma("unroll") for (int n = 0; n < 2; ++n) _Pragma("unroll") for (int k = 0; k < 2; ++k) \
;         acc[ai][bj][m][n] = __builtin_amdgcn_mfma_f32_16x16x32_bf16(Bt[n][k], At[m][k], acc[ai][bj][m][n], 0, 0, 0); __builtin_amdgcn_s_setprio(0); } while (0)
; #define PG8_WAIT_V(n) asm volatile("s_waitcnt vmcnt(" #n ")" ::: "memory")
; #define PG8_WAIT_L(n) asm volatile("s_waitcnt lgkmcnt(" #n ")" ::: "memory")
; #define PG8_BAR __builtin_amdgcn_s_barrier()
; #define PG8_SCHED __builtin_amdgcn_sched_barrier(0)
; template <class Epi, bool PERM = true, bool DBLK = false>
; __device__ __forceinline__ void gemm_phase(LAS unsigned char* lds, const Gemm g, const StaticOrder& S, const Epi& E, const int tid) {
;     ...
;             PG8_LDB(B0, 0, 0); PG8_LDB(B1, 0, 1); PG8_SCHED; PG8_LDA(At, 0, 0); PG8_STAGE(PG8_SA(1, 1), a1 + hstep, voffA);
;             PG8_WAIT_V(8); PG8_WAIT_L(0); PG8_BAR; PG8_MMA(0, 0, At, B0); PG8_MMA(0, 1, At, B1); PG8_BAR; PG8_SCHED;
;     ...
;             PG8_LDA(At, 1, 1); PG8_STAGE(PG8_SB(1, 0), b3, voffB); PG8_STAGE(PG8_SB(1, 1), b3 + hstep, voffB); PG8_STAGE(PG8_SA(1, 0), a3, voffA);
;             PG8_WAIT_V(8); PG8_WAIT_L(0); PG8_BAR; PG8_MMA(1, 0, At, B0); PG8_MMA(1, 1, At, B1); PG8_BAR; PG8_SCHED;
	s_add_i32 s75, s75, s34
	s_mov_b64 s[82:83], 0x180
	s_add_i32 s73, s75, 0x2000
	v_lshl_add_u64 v[194:195], v[194:195], 0, s[82:83]
	s_mov_b32 m0, s75
	s_add_u32 s78, s28, 0x10180
	ds_read_b128 v[170:173], v137 offset:49152
	ds_read_b128 v[174:177], v137 offset:50176
	ds_read_b128 v[178:181], v137 offset:51200
	ds_read_b128 v[182:185], v137 offset:52224
	ds_read_b128 v[186:189], v137 offset:53248
	ds_read_b128 v[190:193], v137 offset:54272
	ds_read_b128 v[202:205], v137 offset:55296
	ds_read_b128 v[206:209], v137 offset:56320
	global_load_lds_dwordx4 v[194:195], off
	v_lshl_add_u64 v[194:195], v[196:197], 0, s[82:83]
	s_mov_b32 m0, s73
	s_addc_u32 s79, s29, 0
	s_add_i32 s28, s64, s34
	global_load_lds_dwordx4 v[194:195], off
	v_lshl_add_u64 v[194:195], s[78:79], 0, v[0:1]
	s_mov_b32 m0, s28
	s_add_i32 s29, s28, 0x2000
	global_load_lds_dwordx4 v[194:195], off
	v_lshl_add_u64 v[194:195], s[78:79], 0, v[130:131]
	s_mov_b32 m0, s29
	s_nop 0
	global_load_lds_dwordx4 v[194:195], off
	v_lshl_add_u64 v[194:195], v[198:199], 0, s[82:83]
	s_mov_b32 m0, s56
	s_nop 0
	global_load_lds_dwordx4 v[194:195], off
	v_lshl_add_u64 v[194:195], v[200:201], 0, s[82:83]
	s_mov_b32 m0, s57
	s_nop 0
	global_load_lds_dwordx4 v[194:195], off
	s_waitcnt vmcnt(8)
	s_waitcnt lgkmcnt(0)
	s_barrier
	s_waitcnt lgkmcnt(0)
	v_mfma_f32_16x16x32_bf16 v[2:5], v[26:29], v[202:205], v[2:5]
	v_mfma_f32_16x16x32_bf16 v[6:9], v[114:117], v[202:205], v[6:9]
	v_mfma_f32_16x16x32_bf16 v[138:141], v[26:29], v[170:173], v[138:141]
	v_mfma_f32_16x16x32_bf16 v[142:145], v[114:117], v[170:173], v[142:145]
	v_mfma_f32_16x16x32_bf16 v[146:149], v[26:29], v[178:181], v[146:149]
	v_mfma_f32_16x16x32_bf16 v[150:153], v[114:117], v[178:181], v[150:153]
	v_mfma_f32_16x16x32_bf16 v[154:157], v[26:29], v[186:189], v[154:157]
	v_mfma_f32_16x16x32_bf16 v[158:161], v[114:117], v[186:189], v[158:161]
	v_mfma_f32_16x16x32_bf16 v[2:5], v[30:33], v[206:209], v[2:5]
	v_mfma_f32_16x16x32_bf16 v[6:9], v[118:121], v[206:209], v[6:9]
	v_mfma_f32_16x16x32_bf16 v[138:141], v[30:33], v[174:177], v[138:141]
	v_mfma_f32_16x16x32_bf16 v[142:145], v[118:121], v[174:177], v[142:145]
	v_mfma_f32_16x16x32_bf16 v[146:149], v[30:33], v[182:185], v[146:149]
	v_mfma_f32_16x16x32_bf16 v[150:153], v[118:121], v[182:185], v[150:153]
	v_mfma_f32_16x16x32_bf16 v[154:157], v[30:33], v[190:193], v[154:157]
	v_mfma_f32_16x16x32_bf16 v[158:161], v[118:121], v[190:193], v[158:161]
	v_mfma_f32_16x16x32_bf16 v[10:13], v[122:125], v[170:173], v[10:13]
	v_mfma_f32_16x16x32_bf16 v[14:17], v[162:165], v[170:173], v[14:17]
	v_mfma_f32_16x16x32_bf16 v[26:29], v[122:125], v[178:181], v[62:65]
	v_mfma_f32_16x16x32_bf16 v[30:33], v[162:165], v[178:181], v[102:105]
	v_mfma_f32_16x16x32_bf16 v[62:65], v[122:125], v[186:189], v[106:109]
	v_mfma_f32_16x16x32_bf16 v[102:105], v[162:165], v[186:189], v[110:113]
	v_mfma_f32_16x16x32_bf16 v[18:21], v[122:125], v[202:205], v[18:21]
	v_mfma_f32_16x16x32_bf16 v[22:25], v[162:165], v[202:205], v[22:25]
	v_mfma_f32_16x16x32_bf16 v[10:13], v[126:129], v[174:177], v[10:13]
	v_mfma_f32_16x16x32_bf16 v[14:17], v[166:169], v[174:177], v[14:17]
	v_mfma_f32_16x16x32_bf16 v[26:29], v[126:129], v[182:185], v[26:29]
	v_mfma_f32_16x16x32_bf16 v[30:33], v[166:169], v[182:185], v[30:33]
	v_mfma_f32_16x16x32_bf16 v[62:65], v[126:129], v[190:193], v[62:65]
	v_mfma_f32_16x16x32_bf16 v[102:105], v[166:169], v[190:193], v[102:105]
	v_mfma_f32_16x16x32_bf16 v[18:21], v[126:129], v[206:209], v[18:21]
	v_mfma_f32_16x16x32_bf16 v[22:25], v[166:169], v[206:209], v[22:25]
	s_barrier
	ds_read_b128 v[106:109], v212
	ds_read_b128 v[110:113], v212 offset:1024
	ds_read_b128 v[114:117], v212 offset:2048
	ds_read_b128 v[118:121], v212 offset:3072
	ds_read_b128 v[122:125], v213
	ds_read_b128 v[126:129], v213 offset:1024
	ds_read_b128 v[162:165], v213 offset:2048
	ds_read_b128 v[166:169], v213 offset:3072
	s_add_u32 s22, s22, 0x10180
	s_addc_u32 s23, s23, 0
	s_mov_b32 m0, s74
	v_lshl_add_u64 v[194:195], s[22:23], 0, v[134:135]
	ds_read_b128 v[170:173], v137
	ds_read_b128 v[174:177], v137 offset:1024
	ds_read_b128 v[178:181], v137 offset:2048
	ds_read_b128 v[182:185], v137 offset:3072
	ds_read_b128 v[186:189], v137 offset:4096
	ds_read_b128 v[190:193], v137 offset:5120
	ds_read_b128 v[202:205], v137 offset:6144
	ds_read_b128 v[206:209], v137 offset:7168
	global_load_lds_dwordx4 v[194:195], off
	v_lshl_add_u64 v[194:195], s[22:23], 0, v[132:133]
	s_mov_b32 m0, s13
	s_nop 0
	global_load_lds_dwordx4 v[194:195], off
	s_waitcnt vmcnt(8)
	s_waitcnt lgkmcnt(0)
	s_barrier
; #define PG8_STAGE(bufoff, gbase, voff) do { _Pragma("unroll") for (int _i = 0; _i < 2; ++_i) \
;         __builtin_amdgcn_global_load_lds((const unsigned*)((const char*)(gbase) + (voff)[_i]), (LAS unsigned*)(lds + (bufoff) + ldsw + _i * 8192), 16, 0, 0); } while (0)
; #define PG8_LDA(dst, b, h) do { _Pragma("unroll") for (int m = 0; m < 4; ++m) _Pragma("unroll") for (int k = 0; k < 2; ++k) dst[m][k] = *(const LAS bf16x8*)(lds + PG8_SA(b, h) + aoff + m * 2048 + k * 1024); } while (0)
; #define PG8_LDB(dst, b, h) do { _Pragma("unroll") for (int n = 0; n < 2; ++n) _Pragma("unroll") for (int k = 0; k < 2; ++k) dst[n][k] = *(const LAS bf16x8*)(lds + PG8_SB(b, h) + boff + n * 2048 + k * 1024); } while (0)
; #define PG8_MMA(ai, bj, At, Bt) do { __builtin_amdgcn_s_setprio(1); _Pragma("unroll") for (int m = 0; m < 4; ++m) _Pragma("unroll") for (int n = 0; n < 2; ++n) _Pragma("unroll") for (int k = 0; k < 2; ++k) \
;         acc[ai][bj][m][n] = __builtin_amdgcn_mfma_f32_16x16x32_bf16(Bt[n][k], At[m][k], acc[ai][bj][m][n], 0, 0, 0); __builtin_amdgcn_s_setprio(0); } while (0)
; #define PG8_WAIT_V(n) asm volatile("s_waitcnt vmcnt(" #n ")" ::: "memory")
; #define PG8_WAIT_L(n) asm volatile("s_waitcnt lgkmcnt(" #n ")" ::: "memory")
; #define PG8_BAR __builtin_amdgcn_s_barrier()
; #define PG8_SCHED __builtin_amdgcn_sched_barrier(0)
; template <class Epi, bool PERM = true, bool DBLK = false>
; __device__ __forceinline__ void gemm_phase(LAS unsigned char* lds, const Gemm g, const StaticOrder& S, const Epi& E, const int tid) {
;     ...
;             PG8_WAIT_V(8); PG8_WAIT_L(0); PG8_BAR; PG8_MMA(0, 0, At, B0); PG8_MMA(0, 1, At, B1); PG8_BAR; PG8_SCHED;
;             PG8_LDA(At, 0, 1); PG8_STAGE(PG8_SB(0, 0), b2, voffB); PG8_STAGE(PG8_SB(0, 1), b2 + hstep, voffB); PG8_STAGE(PG8_SA(0, 0), a2, voffA);
;             PG8_WAIT_V(8); PG8_WAIT_L(0); PG8_BAR; PG8_MMA(1, 0, At, B0); PG8_MMA(1, 1, At, B1); PG8_BAR; PG8_SCHED;
;             PG8_LDB(B0, 1, 0); PG8_LDB(B1, 1, 1); PG8_SCHED; PG8_LDA(At, 1, 0); PG8_STAGE(PG8_SA(0, 1), a2 + hstep, voffA);
	s_waitcnt lgkmcnt(0)
	v_mfma_f32_16x16x32_bf16 v[66:69], v[106:109], v[170:173], v[66:69]
	v_mfma_f32_16x16x32_bf16 v[70:73], v[114:117], v[170:173], v[70:73]
	v_mfma_f32_16x16x32_bf16 v[74:77], v[106:109], v[178:181], v[74:77]
	v_mfma_f32_16x16x32_bf16 v[78:81], v[114:117], v[178:181], v[78:81]
	v_mfma_f32_16x16x32_bf16 v[82:85], v[106:109], v[186:189], v[82:85]
	v_mfma_f32_16x16x32_bf16 v[86:89], v[114:117], v[186:189], v[86:89]
	v_mfma_f32_16x16x32_bf16 v[90:93], v[106:109], v[202:205], v[90:93]
	v_mfma_f32_16x16x32_bf16 v[66:69], v[110:113], v[174:177], v[66:69]
	v_mfma_f32_16x16x32_bf16 v[70:73], v[118:121], v[174:177], v[70:73]
	v_mfma_f32_16x16x32_bf16 v[74:77], v[110:113], v[182:185], v[74:77]
	v_mfma_f32_16x16x32_bf16 v[78:81], v[118:121], v[182:185], v[78:81]
	v_mfma_f32_16x16x32_bf16 v[82:85], v[110:113], v[190:193], v[82:85]
	v_mfma_f32_16x16x32_bf16 v[86:89], v[118:121], v[190:193], v[86:89]
	v_mfma_f32_16x16x32_bf16 v[210:213], v[110:113], v[206:209], v[90:93]
	v_mfma_f32_16x16x32_bf16 v[90:93], v[114:117], v[202:205], v[94:97]
	v_mfma_f32_16x16x32_bf16 v[214:217], v[118:121], v[206:209], v[90:93]
	v_mfma_f32_16x16x32_bf16 v[90:93], v[122:125], v[170:173], v[98:101]
	v_mfma_f32_16x16x32_bf16 v[34:37], v[162:165], v[170:173], v[34:37]
	v_mfma_f32_16x16x32_bf16 v[38:41], v[122:125], v[178:181], v[38:41]
	v_mfma_f32_16x16x32_bf16 v[42:45], v[162:165], v[178:181], v[42:45]
	v_mfma_f32_16x16x32_bf16 v[46:49], v[122:125], v[186:189], v[46:49]
	v_mfma_f32_16x16x32_bf16 v[50:53], v[162:165], v[186:189], v[50:53]
	v_mfma_f32_16x16x32_bf16 v[54:57], v[122:125], v[202:205], v[54:57]
	v_mfma_f32_16x16x32_bf16 v[98:101], v[126:129], v[174:177], v[90:93]
	v_mfma_f32_16x16x32_bf16 v[34:37], v[166:169], v[174:177], v[34:37]
	v_mfma_f32_16x16x32_bf16 v[38:41], v[126:129], v[182:185], v[38:41]
	v_mfma_f32_16x16x32_bf16 v[42:45], v[166:169], v[182:185], v[42:45]
	v_mfma_f32_16x16x32_bf16 v[46:49], v[126:129], v[190:193], v[46:49]
	v_mfma_f32_16x16x32_bf16 v[50:53], v[166:169], v[190:193], v[50:53]
	v_mfma_f32_16x16x32_bf16 v[54:57], v[126:129], v[206:209], v[54:57]
	v_mfma_f32_16x16x32_bf16 v[58:61], v[162:165], v[202:205], v[58:61]
	v_mfma_f32_16x16x32_bf16 v[170:173], v[166:169], v[206:209], v[58:61]
	s_barrier
	s_mov_b32 m0, s72
	v_lshl_add_u64 v[252:253], s[26:27], 0, v[0:1]
	s_add_u32 s22, s26, 0x10000
	s_nop 1
	ds_read_b128 v[58:61], v137 offset:16384
	ds_read_b128 v[90:93], v137 offset:17408
	ds_read_b128 v[94:97], v137 offset:18432
	ds_read_b128 v[174:177], v137 offset:19456
	ds_read_b128 v[178:181], v137 offset:20480
	ds_read_b128 v[182:185], v137 offset:21504
	ds_read_b128 v[186:189], v137 offset:22528
	ds_read_b128 v[190:193], v137 offset:23552
	global_load_lds_dwordx4 v[252:253], off
	v_lshl_add_u64 v[232:233], s[26:27], 0, v[130:131]
	s_mov_b32 m0, s15
	s_addc_u32 s23, s27, 0
	global_load_lds_dwordx4 v[232:233], off
	v_lshl_add_u64 v[194:195], s[22:23], 0, v[0:1]
	s_mov_b32 m0, s66
	v_lshl_add_u64 v[230:231], s[30:31], 0, v[134:135]
	global_load_lds_dwordx4 v[194:195], off
	v_lshl_add_u64 v[194:195], s[22:23], 0, v[130:131]
	s_mov_b32 m0, s67
	v_lshl_add_u64 v[234:235], s[30:31], 0, v[132:133]
	global_load_lds_dwordx4 v[194:195], off
	s_mov_b32 m0, s35
	s_nop 0
	global_load_lds_dwordx4 v[230:231], off
	s_mov_b32 m0, s36
	s_nop 0
	global_load_lds_dwordx4 v[234:235], off
	s_waitcnt vmcnt(8)
	s_waitcnt lgkmcnt(0)
	s_barrier
	s_waitcnt lgkmcnt(0)
	v_mfma_f32_16x16x32_bf16 v[2:5], v[106:109], v[186:189], v[2:5]
	v_mfma_f32_16x16x32_bf16 v[6:9], v[114:117], v[186:189], v[6:9]
	v_mfma_f32_16x16x32_bf16 v[138:141], v[106:109], v[58:61], v[138:141]
	v_mfma_f32_16x16x32_bf16 v[142:145], v[114:117], v[58:61], v[142:145]
	v_mfma_f32_16x16x32_bf16 v[146:149], v[106:109], v[94:97], v[146:149]
	v_mfma_f32_16x16x32_bf16 v[150:153], v[114:117], v[94:97], v[150:153]
	v_mfma_f32_16x16x32_bf16 v[154:157], v[106:109], v[178:181], v[154:157]
	v_mfma_f32_16x16x32_bf16 v[158:161], v[114:117], v[178:181], v[158:161]
	v_mfma_f32_16x16x32_bf16 v[2:5], v[110:113], v[190:193], v[2:5]
	v_mfma_f32_16x16x32_bf16 v[6:9], v[118:121], v[190:193], v[6:9]
	v_mfma_f32_16x16x32_bf16 v[138:141], v[110:113], v[90:93], v[138:141]
	v_mfma_f32_16x16x32_bf16 v[142:145], v[118:121], v[90:93], v[142:145]
	v_mfma_f32_16x16x32_bf16 v[146:149], v[110:113], v[174:177], v[146:149]
	v_mfma_f32_16x16x32_bf16 v[150:153], v[118:121], v[174:177], v[150:153]
	v_mfma_f32_16x16x32_bf16 v[154:157], v[110:113], v[182:185], v[154:157]
	v_mfma_f32_16x16x32_bf16 v[158:161], v[118:121], v[182:185], v[158:161]
	v_mfma_f32_16x16x32_bf16 v[26:29], v[122:125], v[94:97], v[26:29]
	v_mfma_f32_16x16x32_bf16 v[202:205], v[126:129], v[174:177], v[26:29]
	v_mfma_f32_16x16x32_bf16 v[26:29], v[162:165], v[94:97], v[30:33]
	v_mfma_f32_16x16x32_bf16 v[174:177], v[166:169], v[174:177], v[26:29]
	v_mfma_f32_16x16x32_bf16 v[26:29], v[122:125], v[178:181], v[62:65]
	v_mfma_f32_16x16x32_bf16 v[10:13], v[122:125], v[58:61], v[10:13]
	v_mfma_f32_16x16x32_bf16 v[14:17], v[162:165], v[58:61], v[14:17]
	v_mfma_f32_16x16x32_bf16 v[206:209], v[126:129], v[182:185], v[26:29]
	v_mfma_f32_16x16x32_bf16 v[26:29], v[162:165], v[178:181], v[102:105]
	v_mfma_f32_16x16x32_bf16 v[18:21], v[122:125], v[186:189], v[18:21]
	v_mfma_f32_16x16x32_bf16 v[10:13], v[126:129], v[90:93], v[10:13]
	v_mfma_f32_16x16x32_bf16 v[14:17], v[166:169], v[90:93], v[14:17]
	v_mfma_f32_16x16x32_bf16 v[178:181], v[166:169], v[182:185], v[26:29]
	v_mfma_f32_16x16x32_bf16 v[182:185], v[126:129], v[190:193], v[18:21]
	v_mfma_f32_16x16x32_bf16 v[18:21], v[162:165], v[186:189], v[22:25]
	v_mfma_f32_16x16x32_bf16 v[162:165], v[166:169], v[190:193], v[18:21]
	s_barrier
; #define PG8_STAGE(bufoff, gbase, voff) do { _Pragma("unroll") for (int _i = 0; _i < 2; ++_i) \
;         __builtin_amdgcn_global_load_lds((const unsigned*)((const char*)(gbase) + (voff)[_i]), (LAS unsigned*)(lds + (bufoff) + ldsw + _i * 8192), 16, 0, 0); } while (0)
; #define PG8_LDA(dst, b, h) do { _Pragma("unroll") for (int m = 0; m < 4; ++m) _Pragma("unroll") for (int k = 0; k < 2; ++k) dst[m][k] = *(const LAS bf16x8*)(lds + PG8_SA(b, h) + aoff + m * 2048 + k * 1024); } while (0)
; #define PG8_LDB(dst, b, h) do { _Pragma("unroll") for (int n = 0; n < 2; ++n) _Pragma("unroll") for (int k = 0; k < 2; ++k) dst[n][k] = *(const LAS bf16x8*)(lds + PG8_SB(b, h) + boff + n * 2048 + k * 1024); } while (0)
; #define PG8_MMA(ai, bj, At, Bt) do { __builtin_amdgcn_s_setprio(1); _Pragma("unroll") for (int m = 0; m < 4; ++m) _Pragma("unroll") for (int n = 0; n < 2; ++n) _Pragma("unroll") for (int k = 0; k < 2; ++k) \
;         acc[ai][bj][m][n] = __builtin_amdgcn_mfma_f32_16x16x32_bf16(Bt[n][k], At[m][k], acc[ai][bj][m][n], 0, 0, 0); __builtin_amdgcn_s_setprio(0); } while (0)
; #define PG8_WAIT_V(n) asm volatile("s_waitcnt vmcnt(" #n ")" ::: "memory")
; #define PG8_WAIT_L(n) asm volatile("s_waitcnt lgkmcnt(" #n ")" ::: "memory")
; #define PG8_BAR __builtin_amdgcn_s_barrier()
; #define PG8_SCHED __builtin_amdgcn_sched_barrier(0)
; template <class Epi, bool PERM = true, bool DBLK = false>
; __device__ __forceinline__ void gemm_phase(LAS unsigned char* lds, const Gemm g, const StaticOrder& S, const Epi& E, const int tid) {
;     ...
;             PG8_LDB(B0, 1, 0); PG8_LDB(B1, 1, 1); PG8_SCHED; PG8_LDA(At, 1, 0); PG8_STAGE(PG8_SA(0, 1), a2 + hstep, voffA);
;             PG8_WAIT_V(8); PG8_WAIT_L(0); PG8_BAR; PG8_MMA(0, 0, At, B0); PG8_MMA(0, 1, At, B1); PG8_BAR; PG8_SCHED;
;             PG8_LDA(At, 1, 1); PG8_STAGE(PG8_SB(1, 0), b3, voffB); PG8_STAGE(PG8_SB(1, 1), b3 + hstep, voffB); PG8_STAGE(PG8_SA(1, 0), a3, voffA);
;             PG8_WAIT_V(8); PG8_WAIT_L(0); PG8_BAR; PG8_MMA(1, 0, At, B0); PG8_MMA(1, 1, At, B1); PG8_BAR; PG8_SCHED;
;         }
;         if (wr == 0) PG8_BAR;
	ds_read_b128 v[102:105], v218
	ds_read_b128 v[166:169], v218 offset:1024
	ds_read_b128 v[186:189], v218 offset:2048
	ds_read_b128 v[190:193], v218 offset:3072
	ds_read_b128 v[218:221], v226
	ds_read_b128 v[222:225], v226 offset:1024
	ds_read_b128 v[236:239], v226 offset:2048
	ds_read_b128 v[240:243], v226 offset:3072
	s_add_u32 s22, s30, 0x10000
	s_addc_u32 s23, s31, 0
	s_mov_b32 m0, s52
	v_lshl_add_u64 v[26:27], s[22:23], 0, v[134:135]
	ds_read_b128 v[18:21], v137 offset:32768
	ds_read_b128 v[22:25], v137 offset:33792
	ds_read_b128 v[110:113], v137 offset:34816
	ds_read_b128 v[244:247], v137 offset:35840
	ds_read_b128 v[248:251], v137 offset:36864
	ds_read_b128 v[226:229], v137 offset:37888
	ds_read_b128 v[194:197], v137 offset:38912
	ds_read_b128 v[198:201], v137 offset:39936
	global_load_lds_dwordx4 v[26:27], off
	v_lshl_add_u64 v[26:27], s[22:23], 0, v[132:133]
	s_mov_b32 m0, s53
	s_nop 0
	global_load_lds_dwordx4 v[26:27], off
	s_waitcnt vmcnt(8)
	s_waitcnt lgkmcnt(0)
	s_barrier
	s_waitcnt lgkmcnt(0)
	v_mfma_f32_16x16x32_bf16 v[26:29], v[102:105], v[18:21], v[66:69]
	v_mfma_f32_16x16x32_bf16 v[114:117], v[166:169], v[22:25], v[26:29]
	v_mfma_f32_16x16x32_bf16 v[26:29], v[186:189], v[18:21], v[70:73]
	v_mfma_f32_16x16x32_bf16 v[118:121], v[190:193], v[22:25], v[26:29]
	v_mfma_f32_16x16x32_bf16 v[26:29], v[102:105], v[110:113], v[74:77]
	v_mfma_f32_16x16x32_bf16 v[90:93], v[166:169], v[244:247], v[26:29]
	v_mfma_f32_16x16x32_bf16 v[26:29], v[186:189], v[110:113], v[78:81]
	v_mfma_f32_16x16x32_bf16 v[94:97], v[190:193], v[244:247], v[26:29]
	v_mfma_f32_16x16x32_bf16 v[26:29], v[102:105], v[248:251], v[82:85]
	v_mfma_f32_16x16x32_bf16 v[58:61], v[166:169], v[226:229], v[26:29]
	v_mfma_f32_16x16x32_bf16 v[26:29], v[186:189], v[248:251], v[86:89]
	v_mfma_f32_16x16x32_bf16 v[62:65], v[190:193], v[226:229], v[26:29]
	v_mfma_f32_16x16x32_bf16 v[26:29], v[102:105], v[194:197], v[210:213]
	v_mfma_f32_16x16x32_bf16 v[30:33], v[186:189], v[194:197], v[214:217]
	v_mfma_f32_16x16x32_bf16 v[26:29], v[166:169], v[198:201], v[26:29]
	v_mfma_f32_16x16x32_bf16 v[30:33], v[190:193], v[198:201], v[30:33]
	v_mfma_f32_16x16x32_bf16 v[66:69], v[218:221], v[18:21], v[98:101]
	v_mfma_f32_16x16x32_bf16 v[18:21], v[236:239], v[18:21], v[34:37]
	v_mfma_f32_16x16x32_bf16 v[126:129], v[240:243], v[22:25], v[18:21]
	v_mfma_f32_16x16x32_bf16 v[18:21], v[218:221], v[110:113], v[38:41]
	v_mfma_f32_16x16x32_bf16 v[106:109], v[222:225], v[244:247], v[18:21]
	v_mfma_f32_16x16x32_bf16 v[18:21], v[236:239], v[110:113], v[42:45]
	v_mfma_f32_16x16x32_bf16 v[110:113], v[240:243], v[244:247], v[18:21]
	v_mfma_f32_16x16x32_bf16 v[18:21], v[218:221], v[248:251], v[46:49]
	v_mfma_f32_16x16x32_bf16 v[74:77], v[222:225], v[226:229], v[18:21]
	v_mfma_f32_16x16x32_bf16 v[18:21], v[236:239], v[248:251], v[50:53]
	v_mfma_f32_16x16x32_bf16 v[78:81], v[240:243], v[226:229], v[18:21]
	v_mfma_f32_16x16x32_bf16 v[18:21], v[218:221], v[194:197], v[54:57]
	v_mfma_f32_16x16x32_bf16 v[42:45], v[222:225], v[198:201], v[18:21]
	v_mfma_f32_16x16x32_bf16 v[18:21], v[236:239], v[194:197], v[170:173]
	v_mfma_f32_16x16x32_bf16 v[122:125], v[222:225], v[22:25], v[66:69]
	v_mfma_f32_16x16x32_bf16 v[46:49], v[240:243], v[198:201], v[18:21]
	s_barrier
	s_mov_b32 m0, s75
	s_nop 2
	v_lshl_add_u64 v[18:19], v[252:253], 0, s[84:85]
	s_add_u32 s22, s26, 0x10080
	ds_read_b128 v[34:37], v137 offset:49152
	ds_read_b128 v[38:41], v137 offset:50176
	ds_read_b128 v[70:73], v137 offset:51200
	ds_read_b128 v[170:173], v137 offset:52224
	ds_read_b128 v[194:197], v137 offset:53248
	ds_read_b128 v[198:201], v137 offset:54272
	ds_read_b128 v[210:213], v137 offset:55296
	ds_read_b128 v[214:217], v137 offset:56320
	global_load_lds_dwordx4 v[18:19], off
	v_lshl_add_u64 v[18:19], v[232:233], 0, s[84:85]
	s_mov_b32 m0, s73
	s_addc_u32 s23, s27, 0
	global_load_lds_dwordx4 v[18:19], off
	v_lshl_add_u64 v[18:19], s[22:23], 0, v[0:1]
	s_mov_b32 m0, s28
	s_nop 0
	global_load_lds_dwordx4 v[18:19], off
	v_lshl_add_u64 v[18:19], s[22:23], 0, v[130:131]
	s_mov_b32 m0, s29
	s_nop 0
	global_load_lds_dwordx4 v[18:19], off
	v_lshl_add_u64 v[18:19], v[230:231], 0, s[84:85]
	s_mov_b32 m0, s56
	s_nop 0
	global_load_lds_dwordx4 v[18:19], off
	v_lshl_add_u64 v[18:19], v[234:235], 0, s[84:85]
	s_mov_b32 m0, s57
	s_nop 0
	global_load_lds_dwordx4 v[18:19], off
	s_waitcnt vmcnt(8)
	s_waitcnt lgkmcnt(0)
	s_barrier
	s_waitcnt lgkmcnt(0)
	v_mfma_f32_16x16x32_bf16 v[18:21], v[102:105], v[34:37], v[138:141]
	v_mfma_f32_16x16x32_bf16 v[82:85], v[166:169], v[38:41], v[18:21]
	v_mfma_f32_16x16x32_bf16 v[18:21], v[186:189], v[34:37], v[142:145]
	v_mfma_f32_16x16x32_bf16 v[86:89], v[190:193], v[38:41], v[18:21]
	v_mfma_f32_16x16x32_bf16 v[18:21], v[102:105], v[70:73], v[146:149]
	v_mfma_f32_16x16x32_bf16 v[50:53], v[166:169], v[170:173], v[18:21]
	v_mfma_f32_16x16x32_bf16 v[18:21], v[186:189], v[70:73], v[150:153]
	v_mfma_f32_16x16x32_bf16 v[54:57], v[190:193], v[170:173], v[18:21]
	v_mfma_f32_16x16x32_bf16 v[18:21], v[102:105], v[194:197], v[154:157]
	v_mfma_f32_16x16x32_bf16 v[22:25], v[186:189], v[194:197], v[158:161]
	v_mfma_f32_16x16x32_bf16 v[2:5], v[102:105], v[210:213], v[2:5]
	v_mfma_f32_16x16x32_bf16 v[6:9], v[186:189], v[210:213], v[6:9]
	v_mfma_f32_16x16x32_bf16 v[18:21], v[166:169], v[198:201], v[18:21]
	v_mfma_f32_16x16x32_bf16 v[22:25], v[190:193], v[198:201], v[22:25]
	v_mfma_f32_16x16x32_bf16 v[2:5], v[166:169], v[214:217], v[2:5]
	v_mfma_f32_16x16x32_bf16 v[6:9], v[190:193], v[214:217], v[6:9]
	v_mfma_f32_16x16x32_bf16 v[10:13], v[218:221], v[34:37], v[10:13]
	v_mfma_f32_16x16x32_bf16 v[98:101], v[222:225], v[38:41], v[10:13]
	v_mfma_f32_16x16x32_bf16 v[10:13], v[236:239], v[34:37], v[14:17]
	v_mfma_f32_16x16x32_bf16 v[102:105], v[240:243], v[38:41], v[10:13]
	v_mfma_f32_16x16x32_bf16 v[10:13], v[218:221], v[70:73], v[202:205]
	v_mfma_f32_16x16x32_bf16 v[66:69], v[222:225], v[170:173], v[10:13]
	v_mfma_f32_16x16x32_bf16 v[10:13], v[236:239], v[70:73], v[174:177]
	v_mfma_f32_16x16x32_bf16 v[70:73], v[240:243], v[170:173], v[10:13]
	v_mfma_f32_16x16x32_bf16 v[10:13], v[218:221], v[194:197], v[206:209]
	v_mfma_f32_16x16x32_bf16 v[34:37], v[222:225], v[198:201], v[10:13]
	v_mfma_f32_16x16x32_bf16 v[10:13], v[236:239], v[194:197], v[178:181]
	v_mfma_f32_16x16x32_bf16 v[38:41], v[240:243], v[198:201], v[10:13]
	v_mfma_f32_16x16x32_bf16 v[10:13], v[218:221], v[210:213], v[182:185]
	v_mfma_f32_16x16x32_bf16 v[14:17], v[236:239], v[210:213], v[162:165]
	v_mfma_f32_16x16x32_bf16 v[10:13], v[222:225], v[214:217], v[10:13]
	v_mfma_f32_16x16x32_bf16 v[14:17], v[240:243], v[214:217], v[14:17]
	s_barrier
	s_andn2_b64 vcc, exec, s[8:9]
	s_cbranch_vccnz .LBB0_300
	s_barrier

; #define PG8_STAGE(bufoff, gbase, voff) do { _Pragma("unroll") for (int _i = 0; _i < 2; ++_i) \
;         __builtin_amdgcn_global_load_lds((const unsigned*)((const char*)(gbase) + (voff)[_i]), (LAS unsigned*)(lds + (bufoff) + ldsw + _i * 8192), 16, 0, 0); } while (0)
; #define PG8_LDA(dst, b, h) do { _Pragma("unroll") for (int m = 0; m < 4; ++m) _Pragma("unroll") for (int k = 0; k < 2; ++k) dst[m][k] = *(const LAS bf16x8*)(lds + PG8_SA(b, h) + aoff + m * 2048 + k * 1024); } while (0)
; #define PG8_LDB(dst, b, h) do { _Pragma("unroll") for (int n = 0; n < 2; ++n) _Pragma("unroll") for (int k = 0; k < 2; ++k) dst[n][k] = *(const LAS bf16x8*)(lds + PG8_SB(b, h) + boff + n * 2048 + k * 1024); } while (0)
; #define PG8_WAIT_V(n) asm volatile("s_waitcnt vmcnt(" #n ")" ::: "memory")
; #define PG8_WAIT_L(n) asm volatile("s_waitcnt lgkmcnt(" #n ")" ::: "memory")
; #define PG8_BAR __builtin_amdgcn_s_barrier()
; template <class Epi, bool PERM = true, bool DBLK = false>
; __device__ __forceinline__ void gemm_phase(LAS unsigned char* lds, const Gemm g, const StaticOrder& S, const Epi& E, const int tid) {
;     ...
;         const bool has_next = S.next(ui + 1, nxt);
;         const char* nA = has_next ? (const char*)g.A + (size_t)nxt.pm * tstep : cA; const char* nB = has_next ? (const char*)g.Bt + (size_t)nxt.pn * tstep : cB;
;         for (int t2 = 0; t2 < (DBLK ? 2 * nt : nt); t2 += 2) {
;             const int t = DBLK ? (t2 >= nt ? t2 - nt : t2) : t2;
;             const bool lastp = (t == nt - 2);
;             const bool last = DBLK ? (t2 == 2 * nt - 2) : lastp;
;             const char* a1 = cA + (size_t)(t + 1) * kstep;
;             const char* a2 = last ? nA : (lastp ? cA : cA + (size_t)(t + 2) * kstep); const char* b2 = last ? nB : (lastp ? cB : cB + (size_t)(t + 2) * kstep);
;             const char* a3 = a2 + kstep; const char* b3 = b2 + kstep;
;             PG8_LDB(B0, 0, 0); PG8_LDB(B1, 0, 1); PG8_SCHED; PG8_LDA(At, 0, 0); PG8_STAGE(PG8_SA(1, 1), a1 + hstep, voffA);
;             PG8_WAIT_V(8); PG8_WAIT_L(0); PG8_BAR; PG8_MMA(0, 0, At, B0); PG8_MMA(0, 1, At, B1); PG8_BAR; PG8_SCHED;
;             PG8_LDA(At, 0, 1); PG8_STAGE(PG8_SB(0, 0), b2, voffB); PG8_STAGE(PG8_SB(0, 1), b2 + hstep, voffB); PG8_STAGE(PG8_SA(0, 0), a2, voffA);
;             PG8_WAIT_V(8); PG8_WAIT_L(0); PG8_BAR; PG8_MMA(1, 0, At, B0); PG8_MMA(1, 1, At, B1); PG8_BAR; PG8_SCHED;
.LBB0_528:
	s_add_u32 s34, s6, s30
	s_addc_u32 s35, s7, s31
	s_add_u32 s34, s34, 0x100
	s_addc_u32 s35, s35, 0
	s_add_u32 s64, s78, s30
	s_addc_u32 s80, s79, s31
	s_add_i32 s81, 0, 0x10000
	s_cmpk_eq_i32 s30, 0x700
	s_cselect_b32 s53, s25, s35
	s_cselect_b32 s52, s86, s34
	s_cselect_b32 s35, s23, s80
	s_cselect_b32 s34, s82, s64
	s_add_i32 s64, 0, 0x14000
	v_add_u32_e32 v146, s81, v235
	v_add_u32_e32 v162, s64, v235
	ds_read_b128 v[134:137], v146
	ds_read_b128 v[138:141], v146 offset:1024
	ds_read_b128 v[142:145], v146 offset:2048
	ds_read_b128 v[146:149], v146 offset:3072
	ds_read_b128 v[150:153], v162
	ds_read_b128 v[154:157], v162 offset:1024
	ds_read_b128 v[158:161], v162 offset:2048
	ds_read_b128 v[162:165], v162 offset:3072
	v_lshl_add_u64 v[198:199], v[132:133], 0, s[30:31]
	s_add_i32 m0, s3, 0xc000
	ds_read_b128 v[166:169], v236
	ds_read_b128 v[170:173], v236 offset:1024
	ds_read_b128 v[174:177], v236 offset:2048
	ds_read_b128 v[178:181], v236 offset:3072
	ds_read_b128 v[182:185], v236 offset:4096
	ds_read_b128 v[186:189], v236 offset:5120
	ds_read_b128 v[190:193], v236 offset:6144
	ds_read_b128 v[194:197], v236 offset:7168
	global_load_lds_dwordx4 v[198:199], off
	v_lshl_add_u64 v[198:199], v[130:131], 0, s[30:31]
	s_add_i32 m0, s3, 0xe000
	s_nop 0
	global_load_lds_dwordx4 v[198:199], off
	s_waitcnt vmcnt(8)
	s_waitcnt lgkmcnt(0)
	s_barrier
	s_waitcnt lgkmcnt(0)
	v_mfma_f32_16x16x32_bf16 v[126:129], v[134:137], v[166:169], v[126:129]
	v_mfma_f32_16x16x32_bf16 v[122:125], v[142:145], v[166:169], v[122:125]
	v_mfma_f32_16x16x32_bf16 v[110:113], v[134:137], v[174:177], v[110:113]
	v_mfma_f32_16x16x32_bf16 v[106:109], v[142:145], v[174:177], v[106:109]
	v_mfma_f32_16x16x32_bf16 v[94:97], v[134:137], v[182:185], v[94:97]
	v_mfma_f32_16x16x32_bf16 v[90:93], v[142:145], v[182:185], v[90:93]
	v_mfma_f32_16x16x32_bf16 v[78:81], v[134:137], v[190:193], v[78:81]
	v_mfma_f32_16x16x32_bf16 v[74:77], v[142:145], v[190:193], v[74:77]
	v_mfma_f32_16x16x32_bf16 v[126:129], v[138:141], v[170:173], v[126:129]
	v_mfma_f32_16x16x32_bf16 v[122:125], v[146:149], v[170:173], v[122:125]
	v_mfma_f32_16x16x32_bf16 v[110:113], v[138:141], v[178:181], v[110:113]
	v_mfma_f32_16x16x32_bf16 v[106:109], v[146:149], v[178:181], v[106:109]
	v_mfma_f32_16x16x32_bf16 v[94:97], v[138:141], v[186:189], v[94:97]
	v_mfma_f32_16x16x32_bf16 v[90:93], v[146:149], v[186:189], v[90:93]
	v_mfma_f32_16x16x32_bf16 v[78:81], v[138:141], v[194:197], v[78:81]
	v_mfma_f32_16x16x32_bf16 v[74:77], v[146:149], v[194:197], v[74:77]
	v_mfma_f32_16x16x32_bf16 v[118:121], v[150:153], v[166:169], v[118:121]
	v_mfma_f32_16x16x32_bf16 v[114:117], v[158:161], v[166:169], v[114:117]
	v_mfma_f32_16x16x32_bf16 v[102:105], v[150:153], v[174:177], v[102:105]
	v_mfma_f32_16x16x32_bf16 v[98:101], v[158:161], v[174:177], v[98:101]
	v_mfma_f32_16x16x32_bf16 v[86:89], v[150:153], v[182:185], v[86:89]
	v_mfma_f32_16x16x32_bf16 v[82:85], v[158:161], v[182:185], v[82:85]
	v_mfma_f32_16x16x32_bf16 v[70:73], v[150:153], v[190:193], v[70:73]
	v_mfma_f32_16x16x32_bf16 v[66:69], v[158:161], v[190:193], v[66:69]
	v_mfma_f32_16x16x32_bf16 v[118:121], v[154:157], v[170:173], v[118:121]
	v_mfma_f32_16x16x32_bf16 v[114:117], v[162:165], v[170:173], v[114:117]
	v_mfma_f32_16x16x32_bf16 v[102:105], v[154:157], v[178:181], v[102:105]
	v_mfma_f32_16x16x32_bf16 v[98:101], v[162:165], v[178:181], v[98:101]
	v_mfma_f32_16x16x32_bf16 v[86:89], v[154:157], v[186:189], v[86:89]
	v_mfma_f32_16x16x32_bf16 v[82:85], v[162:165], v[186:189], v[82:85]
	v_mfma_f32_16x16x32_bf16 v[70:73], v[154:157], v[194:197], v[70:73]
	v_mfma_f32_16x16x32_bf16 v[66:69], v[162:165], v[194:197], v[66:69]
	s_barrier
	s_add_i32 s80, s81, s54
	v_lshl_add_u64 v[198:199], s[34:35], 0, v[0:1]
	s_mov_b32 m0, s80
	ds_read_b128 v[166:169], v236 offset:16384
	ds_read_b128 v[170:173], v236 offset:17408
	ds_read_b128 v[174:177], v236 offset:18432
	ds_read_b128 v[178:181], v236 offset:19456
	ds_read_b128 v[182:185], v236 offset:20480
	ds_read_b128 v[186:189], v236 offset:21504
	ds_read_b128 v[190:193], v236 offset:22528
	ds_read_b128 v[194:197], v236 offset:23552
	global_load_lds_dwordx4 v[198:199], off
	s_add_i32 m0, s80, 0x2000
	s_add_u32 s80, s34, 0x40000
	v_lshl_add_u64 v[200:201], s[34:35], 0, v[202:203]
	s_addc_u32 s81, s35, 0
	s_add_i32 s64, s64, s54
	global_load_lds_dwordx4 v[200:201], off
	v_lshl_add_u64 v[208:209], s[80:81], 0, v[0:1]
	s_mov_b32 m0, s64
	v_lshl_add_u64 v[210:211], s[52:53], 0, v[202:203]
	global_load_lds_dwordx4 v[208:209], off
	v_lshl_add_u64 v[208:209], s[80:81], 0, v[202:203]
	s_add_i32 m0, s64, 0x2000
	s_nop 0
	global_load_lds_dwordx4 v[208:209], off
	v_lshl_add_u64 v[208:209], s[52:53], 0, v[0:1]
	s_mov_b32 m0, s3
	s_nop 0
	global_load_lds_dwordx4 v[208:209], off
	s_mov_b32 m0, s55
	s_nop 0
	global_load_lds_dwordx4 v[210:211], off
	s_waitcnt vmcnt(8)
	s_waitcnt lgkmcnt(0)
	s_barrier
; #define PG8_STAGE(bufoff, gbase, voff) do { _Pragma("unroll") for (int _i = 0; _i < 2; ++_i) \
;         __builtin_amdgcn_global_load_lds((const unsigned*)((const char*)(gbase) + (voff)[_i]), (LAS unsigned*)(lds + (bufoff) + ldsw + _i * 8192), 16, 0, 0); } while (0)
; #define PG8_LDA(dst, b, h) do { _Pragma("unroll") for (int m = 0; m < 4; ++m) _Pragma("unroll") for (int k = 0; k < 2; ++k) dst[m][k] = *(const LAS bf16x8*)(lds + PG8_SA(b, h) + aoff + m * 2048 + k * 1024); } while (0)
; #define PG8_LDB(dst, b, h) do { _Pragma("unroll") for (int n = 0; n < 2; ++n) _Pragma("unroll") for (int k = 0; k < 2; ++k) dst[n][k] = *(const LAS bf16x8*)(lds + PG8_SB(b, h) + boff + n * 2048 + k * 1024); } while (0)
; #define PG8_MMA(ai, bj, At, Bt) do { __builtin_amdgcn_s_setprio(1); _Pragma("unroll") for (int m = 0; m < 4; ++m) _Pragma("unroll") for (int n = 0; n < 2; ++n) _Pragma("unroll") for (int k = 0; k < 2; ++k) \
;         acc[ai][bj][m][n] = __builtin_amdgcn_mfma_f32_16x16x32_bf16(Bt[n][k], At[m][k], acc[ai][bj][m][n], 0, 0, 0); __builtin_amdgcn_s_setprio(0); } while (0)
; #define PG8_WAIT_V(n) asm volatile("s_waitcnt vmcnt(" #n ")" ::: "memory")
; #define PG8_WAIT_L(n) asm volatile("s_waitcnt lgkmcnt(" #n ")" ::: "memory")
; #define PG8_BAR __builtin_amdgcn_s_barrier()
; #define PG8_SCHED __builtin_amdgcn_sched_barrier(0)
; template <class Epi, bool PERM = true, bool DBLK = false>
; __device__ __forceinline__ void gemm_phase(LAS unsigned char* lds, const Gemm g, const StaticOrder& S, const Epi& E, const int tid) {
;     ...
;             PG8_LDA(At, 0, 1); PG8_STAGE(PG8_SB(0, 0), b2, voffB); PG8_STAGE(PG8_SB(0, 1), b2 + hstep, voffB); PG8_STAGE(PG8_SA(0, 0), a2, voffA);
;             PG8_WAIT_V(8); PG8_WAIT_L(0); PG8_BAR; PG8_MMA(1, 0, At, B0); PG8_MMA(1, 1, At, B1); PG8_BAR; PG8_SCHED;
;             PG8_LDB(B0, 1, 0); PG8_LDB(B1, 1, 1); PG8_SCHED; PG8_LDA(At, 1, 0); PG8_STAGE(PG8_SA(0, 1), a2 + hstep, voffA);
;             PG8_WAIT_V(8); PG8_WAIT_L(0); PG8_BAR; PG8_MMA(0, 0, At, B0); PG8_MMA(0, 1, At, B1); PG8_BAR; PG8_SCHED;
	s_waitcnt lgkmcnt(0)
	v_mfma_f32_16x16x32_bf16 v[62:65], v[134:137], v[166:169], v[62:65]
	v_mfma_f32_16x16x32_bf16 v[58:61], v[142:145], v[166:169], v[58:61]
	v_mfma_f32_16x16x32_bf16 v[46:49], v[134:137], v[174:177], v[46:49]
	v_mfma_f32_16x16x32_bf16 v[42:45], v[142:145], v[174:177], v[42:45]
	v_mfma_f32_16x16x32_bf16 v[30:33], v[134:137], v[182:185], v[30:33]
	v_mfma_f32_16x16x32_bf16 v[26:29], v[142:145], v[182:185], v[26:29]
	v_mfma_f32_16x16x32_bf16 v[14:17], v[134:137], v[190:193], v[14:17]
	v_mfma_f32_16x16x32_bf16 v[10:13], v[142:145], v[190:193], v[10:13]
	v_mfma_f32_16x16x32_bf16 v[62:65], v[138:141], v[170:173], v[62:65]
	v_mfma_f32_16x16x32_bf16 v[58:61], v[146:149], v[170:173], v[58:61]
	v_mfma_f32_16x16x32_bf16 v[46:49], v[138:141], v[178:181], v[46:49]
	v_mfma_f32_16x16x32_bf16 v[42:45], v[146:149], v[178:181], v[42:45]
	v_mfma_f32_16x16x32_bf16 v[30:33], v[138:141], v[186:189], v[30:33]
	v_mfma_f32_16x16x32_bf16 v[26:29], v[146:149], v[186:189], v[26:29]
	v_mfma_f32_16x16x32_bf16 v[14:17], v[138:141], v[194:197], v[14:17]
	v_mfma_f32_16x16x32_bf16 v[10:13], v[146:149], v[194:197], v[10:13]
	v_mfma_f32_16x16x32_bf16 v[54:57], v[150:153], v[166:169], v[54:57]
	v_mfma_f32_16x16x32_bf16 v[50:53], v[158:161], v[166:169], v[50:53]
	v_mfma_f32_16x16x32_bf16 v[38:41], v[150:153], v[174:177], v[38:41]
	v_mfma_f32_16x16x32_bf16 v[34:37], v[158:161], v[174:177], v[34:37]
	v_mfma_f32_16x16x32_bf16 v[22:25], v[150:153], v[182:185], v[22:25]
	v_mfma_f32_16x16x32_bf16 v[18:21], v[158:161], v[182:185], v[18:21]
	v_mfma_f32_16x16x32_bf16 v[6:9], v[150:153], v[190:193], v[6:9]
	v_mfma_f32_16x16x32_bf16 v[2:5], v[158:161], v[190:193], v[2:5]
	v_mfma_f32_16x16x32_bf16 v[54:57], v[154:157], v[170:173], v[54:57]
	v_mfma_f32_16x16x32_bf16 v[50:53], v[162:165], v[170:173], v[50:53]
	v_mfma_f32_16x16x32_bf16 v[38:41], v[154:157], v[178:181], v[38:41]
	v_mfma_f32_16x16x32_bf16 v[34:37], v[162:165], v[178:181], v[34:37]
	v_mfma_f32_16x16x32_bf16 v[22:25], v[154:157], v[186:189], v[22:25]
	v_mfma_f32_16x16x32_bf16 v[18:21], v[162:165], v[186:189], v[18:21]
	v_mfma_f32_16x16x32_bf16 v[6:9], v[154:157], v[194:197], v[6:9]
	v_mfma_f32_16x16x32_bf16 v[2:5], v[162:165], v[194:197], v[2:5]
	s_barrier
	s_add_i32 s64, 0, 0x18000
	s_add_i32 s80, 0, 0x1c000
	v_add_u32_e32 v146, s64, v235
	v_add_u32_e32 v162, s80, v235
	ds_read_b128 v[134:137], v146
	ds_read_b128 v[138:141], v146 offset:1024
	ds_read_b128 v[142:145], v146 offset:2048
	ds_read_b128 v[146:149], v146 offset:3072
	ds_read_b128 v[150:153], v162
	ds_read_b128 v[154:157], v162 offset:1024
	ds_read_b128 v[158:161], v162 offset:2048
	ds_read_b128 v[162:165], v162 offset:3072
	s_add_u32 s52, s52, 0x40000
	s_addc_u32 s53, s53, 0
	s_mov_b32 m0, s56
	v_lshl_add_u64 v[212:213], s[52:53], 0, v[0:1]
	ds_read_b128 v[166:169], v236 offset:32768
	ds_read_b128 v[170:173], v236 offset:33792
	ds_read_b128 v[174:177], v236 offset:34816
	ds_read_b128 v[178:181], v236 offset:35840
	ds_read_b128 v[182:185], v236 offset:36864
	ds_read_b128 v[186:189], v236 offset:37888
	ds_read_b128 v[190:193], v236 offset:38912
	ds_read_b128 v[194:197], v236 offset:39936
	global_load_lds_dwordx4 v[212:213], off
	v_lshl_add_u64 v[212:213], s[52:53], 0, v[202:203]
	s_mov_b32 m0, s57
	s_nop 0
	global_load_lds_dwordx4 v[212:213], off
	s_waitcnt vmcnt(8)
	s_waitcnt lgkmcnt(0)
	s_barrier
	s_waitcnt lgkmcnt(0)
	v_mfma_f32_16x16x32_bf16 v[126:129], v[134:137], v[166:169], v[126:129]
	v_mfma_f32_16x16x32_bf16 v[122:125], v[142:145], v[166:169], v[122:125]
	v_mfma_f32_16x16x32_bf16 v[110:113], v[134:137], v[174:177], v[110:113]
	v_mfma_f32_16x16x32_bf16 v[106:109], v[142:145], v[174:177], v[106:109]
	v_mfma_f32_16x16x32_bf16 v[94:97], v[134:137], v[182:185], v[94:97]
	v_mfma_f32_16x16x32_bf16 v[90:93], v[142:145], v[182:185], v[90:93]
	v_mfma_f32_16x16x32_bf16 v[78:81], v[134:137], v[190:193], v[78:81]
	v_mfma_f32_16x16x32_bf16 v[74:77], v[142:145], v[190:193], v[74:77]
	v_mfma_f32_16x16x32_bf16 v[126:129], v[138:141], v[170:173], v[126:129]
	v_mfma_f32_16x16x32_bf16 v[122:125], v[146:149], v[170:173], v[122:125]
	v_mfma_f32_16x16x32_bf16 v[110:113], v[138:141], v[178:181], v[110:113]
	v_mfma_f32_16x16x32_bf16 v[106:109], v[146:149], v[178:181], v[106:109]
	v_mfma_f32_16x16x32_bf16 v[94:97], v[138:141], v[186:189], v[94:97]
	v_mfma_f32_16x16x32_bf16 v[90:93], v[146:149], v[186:189], v[90:93]
	v_mfma_f32_16x16x32_bf16 v[78:81], v[138:141], v[194:197], v[78:81]
	v_mfma_f32_16x16x32_bf16 v[74:77], v[146:149], v[194:197], v[74:77]
	v_mfma_f32_16x16x32_bf16 v[118:121], v[150:153], v[166:169], v[118:121]
	v_mfma_f32_16x16x32_bf16 v[114:117], v[158:161], v[166:169], v[114:117]
	v_mfma_f32_16x16x32_bf16 v[102:105], v[150:153], v[174:177], v[102:105]
	v_mfma_f32_16x16x32_bf16 v[98:101], v[158:161], v[174:177], v[98:101]
	v_mfma_f32_16x16x32_bf16 v[86:89], v[150:153], v[182:185], v[86:89]
	v_mfma_f32_16x16x32_bf16 v[82:85], v[158:161], v[182:185], v[82:85]
	v_mfma_f32_16x16x32_bf16 v[70:73], v[150:153], v[190:193], v[70:73]
	v_mfma_f32_16x16x32_bf16 v[66:69], v[158:161], v[190:193], v[66:69]
	v_mfma_f32_16x16x32_bf16 v[118:121], v[154:157], v[170:173], v[118:121]
	v_mfma_f32_16x16x32_bf16 v[114:117], v[162:165], v[170:173], v[114:117]
	v_mfma_f32_16x16x32_bf16 v[102:105], v[154:157], v[178:181], v[102:105]
	v_mfma_f32_16x16x32_bf16 v[98:101], v[162:165], v[178:181], v[98:101]
	v_mfma_f32_16x16x32_bf16 v[86:89], v[154:157], v[186:189], v[86:89]
	v_mfma_f32_16x16x32_bf16 v[82:85], v[162:165], v[186:189], v[82:85]
	v_mfma_f32_16x16x32_bf16 v[70:73], v[154:157], v[194:197], v[70:73]
	v_mfma_f32_16x16x32_bf16 v[66:69], v[162:165], v[194:197], v[66:69]
	s_barrier
; #define PG8_STAGE(bufoff, gbase, voff) do { _Pragma("unroll") for (int _i = 0; _i < 2; ++_i) \
;         __builtin_amdgcn_global_load_lds((const unsigned*)((const char*)(gbase) + (voff)[_i]), (LAS unsigned*)(lds + (bufoff) + ldsw + _i * 8192), 16, 0, 0); } while (0)
; #define PG8_LDA(dst, b, h) do { _Pragma("unroll") for (int m = 0; m < 4; ++m) _Pragma("unroll") for (int k = 0; k < 2; ++k) dst[m][k] = *(const LAS bf16x8*)(lds + PG8_SA(b, h) + aoff + m * 2048 + k * 1024); } while (0)
; #define PG8_MMA(ai, bj, At, Bt) do { __builtin_amdgcn_s_setprio(1); _Pragma("unroll") for (int m = 0; m < 4; ++m) _Pragma("unroll") for (int n = 0; n < 2; ++n) _Pragma("unroll") for (int k = 0; k < 2; ++k) \
;         acc[ai][bj][m][n] = __builtin_amdgcn_mfma_f32_16x16x32_bf16(Bt[n][k], At[m][k], acc[ai][bj][m][n], 0, 0, 0); __builtin_amdgcn_s_setprio(0); } while (0)
; #define PG8_WAIT_V(n) asm volatile("s_waitcnt vmcnt(" #n ")" ::: "memory")
; #define PG8_WAIT_L(n) asm volatile("s_waitcnt lgkmcnt(" #n ")" ::: "memory")
; #define PG8_BAR __builtin_amdgcn_s_barrier()
; #define PG8_SCHED __builtin_amdgcn_sched_barrier(0)
; template <class Epi, bool PERM = true, bool DBLK = false>
; __device__ __forceinline__ void gemm_phase(LAS unsigned char* lds, const Gemm g, const StaticOrder& S, const Epi& E, const int tid) {
;     ...
;             PG8_LDA(At, 1, 1); PG8_STAGE(PG8_SB(1, 0), b3, voffB); PG8_STAGE(PG8_SB(1, 1), b3 + hstep, voffB); PG8_STAGE(PG8_SA(1, 0), a3, voffA);
;             PG8_WAIT_V(8); PG8_WAIT_L(0); PG8_BAR; PG8_MMA(1, 0, At, B0); PG8_MMA(1, 1, At, B1); PG8_BAR; PG8_SCHED;
;         }
;         if (wr == 0) PG8_BAR;
	s_add_i32 s52, s64, s54
	v_lshl_add_u64 v[198:199], v[198:199], 0, s[84:85]
	s_mov_b32 m0, s52
	ds_read_b128 v[166:169], v236 offset:49152
	ds_read_b128 v[170:173], v236 offset:50176
	ds_read_b128 v[174:177], v236 offset:51200
	ds_read_b128 v[178:181], v236 offset:52224
	ds_read_b128 v[182:185], v236 offset:53248
	ds_read_b128 v[186:189], v236 offset:54272
	ds_read_b128 v[190:193], v236 offset:55296
	ds_read_b128 v[194:197], v236 offset:56320
	global_load_lds_dwordx4 v[198:199], off
	s_add_i32 m0, s52, 0x2000
	s_add_u32 s34, s34, 0x40080
	v_lshl_add_u64 v[198:199], v[200:201], 0, s[84:85]
	s_addc_u32 s35, s35, 0
	s_add_i32 s52, s80, s54
	global_load_lds_dwordx4 v[198:199], off
	v_lshl_add_u64 v[198:199], s[34:35], 0, v[0:1]
	s_mov_b32 m0, s52
	s_nop 0
	global_load_lds_dwordx4 v[198:199], off
	v_lshl_add_u64 v[198:199], s[34:35], 0, v[202:203]
	s_add_i32 m0, s52, 0x2000
	s_nop 0
	global_load_lds_dwordx4 v[198:199], off
	v_lshl_add_u64 v[198:199], v[208:209], 0, s[84:85]
	s_mov_b32 m0, s66
	s_nop 0
	global_load_lds_dwordx4 v[198:199], off
	v_lshl_add_u64 v[198:199], v[210:211], 0, s[84:85]
	s_mov_b32 m0, s67
	s_nop 0
	global_load_lds_dwordx4 v[198:199], off
	s_waitcnt vmcnt(8)
	s_waitcnt lgkmcnt(0)
	s_barrier
	s_waitcnt lgkmcnt(0)
	v_mfma_f32_16x16x32_bf16 v[62:65], v[134:137], v[166:169], v[62:65]
	v_mfma_f32_16x16x32_bf16 v[58:61], v[142:145], v[166:169], v[58:61]
	v_mfma_f32_16x16x32_bf16 v[46:49], v[134:137], v[174:177], v[46:49]
	v_mfma_f32_16x16x32_bf16 v[42:45], v[142:145], v[174:177], v[42:45]
	v_mfma_f32_16x16x32_bf16 v[30:33], v[134:137], v[182:185], v[30:33]
	v_mfma_f32_16x16x32_bf16 v[26:29], v[142:145], v[182:185], v[26:29]
	v_mfma_f32_16x16x32_bf16 v[14:17], v[134:137], v[190:193], v[14:17]
	v_mfma_f32_16x16x32_bf16 v[10:13], v[142:145], v[190:193], v[10:13]
	v_mfma_f32_16x16x32_bf16 v[62:65], v[138:141], v[170:173], v[62:65]
	v_mfma_f32_16x16x32_bf16 v[58:61], v[146:149], v[170:173], v[58:61]
	v_mfma_f32_16x16x32_bf16 v[46:49], v[138:141], v[178:181], v[46:49]
	v_mfma_f32_16x16x32_bf16 v[42:45], v[146:149], v[178:181], v[42:45]
	v_mfma_f32_16x16x32_bf16 v[30:33], v[138:141], v[186:189], v[30:33]
	v_mfma_f32_16x16x32_bf16 v[26:29], v[146:149], v[186:189], v[26:29]
	v_mfma_f32_16x16x32_bf16 v[14:17], v[138:141], v[194:197], v[14:17]
	v_mfma_f32_16x16x32_bf16 v[10:13], v[146:149], v[194:197], v[10:13]
	v_mfma_f32_16x16x32_bf16 v[54:57], v[150:153], v[166:169], v[54:57]
	v_mfma_f32_16x16x32_bf16 v[50:53], v[158:161], v[166:169], v[50:53]
	v_mfma_f32_16x16x32_bf16 v[38:41], v[150:153], v[174:177], v[38:41]
	v_mfma_f32_16x16x32_bf16 v[34:37], v[158:161], v[174:177], v[34:37]
	v_mfma_f32_16x16x32_bf16 v[22:25], v[150:153], v[182:185], v[22:25]
	v_mfma_f32_16x16x32_bf16 v[18:21], v[158:161], v[182:185], v[18:21]
	v_mfma_f32_16x16x32_bf16 v[6:9], v[150:153], v[190:193], v[6:9]
	v_mfma_f32_16x16x32_bf16 v[2:5], v[158:161], v[190:193], v[2:5]
	v_mfma_f32_16x16x32_bf16 v[54:57], v[154:157], v[170:173], v[54:57]
	v_mfma_f32_16x16x32_bf16 v[50:53], v[162:165], v[170:173], v[50:53]
	v_mfma_f32_16x16x32_bf16 v[38:41], v[154:157], v[178:181], v[38:41]
	v_mfma_f32_16x16x32_bf16 v[34:37], v[162:165], v[178:181], v[34:37]
	v_mfma_f32_16x16x32_bf16 v[22:25], v[154:157], v[186:189], v[22:25]
	v_mfma_f32_16x16x32_bf16 v[18:21], v[162:165], v[186:189], v[18:21]
	v_mfma_f32_16x16x32_bf16 v[6:9], v[154:157], v[194:197], v[6:9]
	v_mfma_f32_16x16x32_bf16 v[2:5], v[162:165], v[194:197], v[2:5]
	s_barrier
	s_add_i32 s83, s83, 2
	s_add_u32 s30, s30, 0x100
	s_addc_u32 s31, s31, 0
	s_cmp_gt_u32 s83, 13
	s_cbranch_scc0 .LBB0_528
	s_and_b64 vcc, exec, s[18:19]
	s_cbranch_vccz .LBB0_531
	s_barrier
